# v37 + P0 generic flat_ stores converted to global_ stores (no lgkmcnt coupling with the LDS transposes)
# baseline (speedup 1.0000x reference)
.LBB0_10:
	s_waitcnt vmcnt(0)
	ds_write2_b32 v74, v6, v7 offset1:1
	ds_write2_b32 v74, v8, v9 offset0:2 offset1:3
	ds_write2_b32 v75, v2, v3 offset1:1
	ds_write2_b32 v76, v4, v5 offset1:1
	ds_write2_b32 v77, v14, v15 offset1:1
	ds_write2_b32 v78, v16, v17 offset1:1
	ds_write2_b32 v79, v10, v11 offset1:1
	ds_write2_b32 v80, v12, v13 offset1:1
	ds_write2_b32 v81, v22, v23 offset1:1
	ds_write2_b32 v82, v24, v25 offset1:1
	ds_write2_b32 v83, v18, v19 offset1:1
	ds_write2_b32 v84, v20, v21 offset1:1
	ds_write2_b32 v85, v30, v31 offset1:1
	ds_write2_b32 v86, v32, v33 offset1:1
	ds_write2_b32 v87, v26, v27 offset1:1
	ds_write2_b32 v88, v28, v29 offset1:1
	s_waitcnt lgkmcnt(0)
	ds_read_b32 v2, v73
	ds_read_b32 v3, v73 offset:132
	ds_read_b32 v4, v73 offset:264
	ds_read_b32 v5, v73 offset:396
	ds_read_b32 v8, v73 offset:528
	ds_read_b32 v9, v73 offset:660
	ds_read_b32 v10, v73 offset:792
	ds_read_b32 v11, v73 offset:924
	s_waitcnt lgkmcnt(0)
	v_bfe_u32 v12, v2, 16, 1
	v_add3_u32 v2, v2, v12, s35
	v_bfe_u32 v12, v3, 16, 1
	v_lshrrev_b32_e32 v2, 16, v2
	v_add3_u32 v3, v3, v12, s35
	v_and_or_b32 v2, v3, s36, v2
	v_bfe_u32 v3, v4, 16, 1
	v_add3_u32 v3, v4, v3, s35
	v_bfe_u32 v4, v5, 16, 1
	v_lshrrev_b32_e32 v3, 16, v3
	v_add3_u32 v4, v5, v4, s35
	v_and_or_b32 v3, v4, s36, v3
	v_bfe_u32 v4, v8, 16, 1
	v_add3_u32 v4, v8, v4, s35
	v_bfe_u32 v5, v9, 16, 1
	v_lshrrev_b32_e32 v4, 16, v4
	v_add3_u32 v5, v9, v5, s35
	v_and_or_b32 v4, v5, s36, v4
	v_bfe_u32 v5, v10, 16, 1
	v_add3_u32 v5, v10, v5, s35
	v_bfe_u32 v8, v11, 16, 1
	s_mul_i32 s0, s46, 0xffffef00
	v_lshrrev_b32_e32 v5, 16, v5
	v_add3_u32 v8, v11, v8, s35
	s_add_i32 s0, s0, s22
	v_and_or_b32 v5, v8, s36, v5
	v_add_u32_e32 v8, s0, v35
	s_ashr_i32 s19, s18, 31
	v_ashrrev_i32_e32 v9, 31, v8
	v_lshl_add_u64 v[6:7], s[18:19], 1, v[66:67]
	v_lshlrev_b64 v[10:11], 12, v[8:9]
	v_lshl_add_u64 v[10:11], v[6:7], 0, v[10:11]
	global_store_dwordx4 v[10:11], v[2:5], off
	ds_read_b32 v2, v73 offset:32
	ds_read_b32 v3, v73 offset:164
	ds_read_b32 v4, v73 offset:296
	ds_read_b32 v5, v73 offset:428
	ds_read_b32 v9, v73 offset:560
	ds_read_b32 v10, v73 offset:692
	ds_read_b32 v11, v73 offset:824
	ds_read_b32 v12, v73 offset:956
	s_waitcnt lgkmcnt(0)
	v_bfe_u32 v13, v2, 16, 1
	v_add3_u32 v2, v2, v13, s35
	v_bfe_u32 v13, v3, 16, 1
	v_lshrrev_b32_e32 v2, 16, v2
	v_add3_u32 v3, v3, v13, s35
	v_and_or_b32 v2, v3, s36, v2
	v_bfe_u32 v3, v4, 16, 1
	v_add3_u32 v3, v4, v3, s35
	v_bfe_u32 v4, v5, 16, 1
	v_lshrrev_b32_e32 v3, 16, v3
	v_add3_u32 v4, v5, v4, s35
	v_and_or_b32 v3, v4, s36, v3
	v_bfe_u32 v4, v9, 16, 1
	v_add3_u32 v4, v9, v4, s35
	v_bfe_u32 v5, v10, 16, 1
	v_lshrrev_b32_e32 v4, 16, v4
	v_add3_u32 v5, v10, v5, s35
	v_and_or_b32 v4, v5, s36, v4
	v_bfe_u32 v5, v11, 16, 1
	v_add_u32_e32 v10, 8, v8
	v_add3_u32 v5, v11, v5, s35
	v_bfe_u32 v9, v12, 16, 1
	v_ashrrev_i32_e32 v11, 31, v10
	v_lshrrev_b32_e32 v5, 16, v5
	v_add3_u32 v9, v12, v9, s35
	v_lshlrev_b64 v[10:11], 12, v[10:11]
	v_and_or_b32 v5, v9, s36, v5
	v_lshl_add_u64 v[10:11], v[6:7], 0, v[10:11]
	global_store_dwordx4 v[10:11], v[2:5], off
	ds_read_b32 v2, v73 offset:64
	ds_read_b32 v3, v73 offset:196
	ds_read_b32 v4, v73 offset:328
	ds_read_b32 v5, v73 offset:460
	ds_read_b32 v9, v73 offset:592
	ds_read_b32 v10, v73 offset:724
	ds_read_b32 v11, v73 offset:856
	ds_read_b32 v12, v73 offset:988
	s_waitcnt lgkmcnt(0)
	v_bfe_u32 v13, v2, 16, 1
	v_add3_u32 v2, v2, v13, s35
	v_bfe_u32 v13, v3, 16, 1
	v_lshrrev_b32_e32 v2, 16, v2
	v_add3_u32 v3, v3, v13, s35
	v_and_or_b32 v2, v3, s36, v2
	v_bfe_u32 v3, v4, 16, 1
	v_add3_u32 v3, v4, v3, s35
	v_bfe_u32 v4, v5, 16, 1
	v_lshrrev_b32_e32 v3, 16, v3
	v_add3_u32 v4, v5, v4, s35
	v_and_or_b32 v3, v4, s36, v3
	v_bfe_u32 v4, v9, 16, 1
	v_add3_u32 v4, v9, v4, s35
	v_bfe_u32 v5, v10, 16, 1
	v_lshrrev_b32_e32 v4, 16, v4
	v_add3_u32 v5, v10, v5, s35
	v_and_or_b32 v4, v5, s36, v4
	v_bfe_u32 v5, v11, 16, 1
	v_add_u32_e32 v10, 16, v8
	v_add3_u32 v5, v11, v5, s35
	v_bfe_u32 v9, v12, 16, 1
	v_ashrrev_i32_e32 v11, 31, v10
	v_lshrrev_b32_e32 v5, 16, v5
	v_add3_u32 v9, v12, v9, s35
	v_lshlrev_b64 v[10:11], 12, v[10:11]
	v_and_or_b32 v5, v9, s36, v5
	v_lshl_add_u64 v[10:11], v[6:7], 0, v[10:11]
	global_store_dwordx4 v[10:11], v[2:5], off
	ds_read_b32 v2, v73 offset:96
	ds_read_b32 v3, v73 offset:228
	ds_read_b32 v4, v73 offset:360
	ds_read_b32 v5, v73 offset:492
	ds_read_b32 v9, v73 offset:624
	ds_read_b32 v10, v73 offset:756
	ds_read_b32 v11, v73 offset:888
	ds_read_b32 v12, v73 offset:1020
	s_waitcnt lgkmcnt(0)
	v_bfe_u32 v13, v2, 16, 1
	v_add3_u32 v2, v2, v13, s35
	v_bfe_u32 v13, v3, 16, 1
	v_lshrrev_b32_e32 v2, 16, v2
	v_add3_u32 v3, v3, v13, s35
	v_and_or_b32 v2, v3, s36, v2
	v_bfe_u32 v3, v4, 16, 1
	v_add3_u32 v3, v4, v3, s35
	v_bfe_u32 v4, v5, 16, 1
	v_lshrrev_b32_e32 v3, 16, v3
	v_add3_u32 v4, v5, v4, s35
	v_and_or_b32 v3, v4, s36, v3
	v_bfe_u32 v4, v9, 16, 1
	v_add3_u32 v4, v9, v4, s35
	v_bfe_u32 v5, v10, 16, 1
	v_lshrrev_b32_e32 v4, 16, v4
	v_add3_u32 v5, v10, v5, s35
	v_and_or_b32 v4, v5, s36, v4
	v_bfe_u32 v5, v11, 16, 1
	v_add3_u32 v5, v11, v5, s35
	v_bfe_u32 v9, v12, 16, 1
	v_lshrrev_b32_e32 v5, 16, v5
	v_add3_u32 v9, v12, v9, s35
	v_add_u32_e32 v8, 24, v8
	v_and_or_b32 v5, v9, s36, v5
	v_ashrrev_i32_e32 v9, 31, v8
	v_lshlrev_b64 v[8:9], 12, v[8:9]
	v_lshl_add_u64 v[6:7], v[6:7], 0, v[8:9]
	global_store_dwordx4 v[6:7], v[2:5], off
	s_waitcnt lgkmcnt(0)

.LBB0_12:
	s_cmpk_gt_i32 s45, 0x10ff
	s_mov_b64 s[6:7], -1
	s_cbranch_scc0 .LBB0_50
	s_cmpk_gt_u32 s45, 0x14ff
	s_cbranch_scc0 .LBB0_47
	s_cmpk_gt_u32 s45, 0x15ff
	s_cbranch_scc0 .LBB0_42
	s_cmpk_gt_u32 s45, 0x16ff
	s_cbranch_scc0 .LBB0_37
	s_cmpk_gt_u32 s45, 0x1eff
	s_cbranch_scc0 .LBB0_34
	s_cmpk_gt_u32 s45, 0x4aff
	s_cbranch_scc0 .LBB0_29
	s_cmpk_gt_u32 s45, 0x60ff
	s_cbranch_scc0 .LBB0_26
	s_and_b32 s18, s22, 0x7e0
	s_cmpk_gt_u32 s45, 0x68ff
	v_or_b32_e32 v90, s18, v35
	v_or_b32_e32 v89, s18, v70
	v_or_b32_e32 v69, s18, v71
	v_or_b32_e32 v68, s18, v72
	s_cbranch_scc0 .LBB0_21
	s_and_b32 s0, s45, 0x7fffffc0
	s_add_i32 s6, s0, 0xffff9700
	v_or_b32_e32 v36, s6, v35
	s_lshl_b32 s0, s18, 2
	v_or_b32_e32 v6, 8, v36
	v_mov_b32_e32 v7, v37
	v_or_b32_e32 v12, 16, v36
	v_mov_b32_e32 v13, v37
	v_or_b32_e32 v14, 24, v36
	v_mov_b32_e32 v15, v37
	v_or_b32_e32 v20, 32, v36
	v_mov_b32_e32 v21, v37
	v_or_b32_e32 v22, 40, v36
	v_mov_b32_e32 v23, v37
	v_lshl_add_u64 v[2:3], v[38:39], 0, s[0:1]
	v_lshlrev_b64 v[4:5], 13, v[36:37]
	v_lshlrev_b64 v[6:7], 13, v[6:7]
	v_lshlrev_b64 v[12:13], 13, v[12:13]
	v_lshlrev_b64 v[14:15], 13, v[14:15]
	v_lshlrev_b64 v[20:21], 13, v[20:21]
	v_lshlrev_b64 v[22:23], 13, v[22:23]
	v_lshl_add_u64 v[4:5], v[2:3], 0, v[4:5]
	v_lshl_add_u64 v[8:9], v[2:3], 0, v[6:7]
	v_lshl_add_u64 v[12:13], v[2:3], 0, v[12:13]
	v_lshl_add_u64 v[16:17], v[2:3], 0, v[14:15]
	v_lshl_add_u64 v[20:21], v[2:3], 0, v[20:21]
	v_lshl_add_u64 v[24:25], v[2:3], 0, v[22:23]
	global_load_dwordx4 v[4:7], v[4:5], off
	s_nop 0
	global_load_dwordx4 v[8:11], v[8:9], off
	s_nop 0
	global_load_dwordx4 v[12:15], v[12:13], off
	s_nop 0
	global_load_dwordx4 v[16:19], v[16:17], off
	s_nop 0
	global_load_dwordx4 v[20:23], v[20:21], off
	s_nop 0
	global_load_dwordx4 v[24:27], v[24:25], off
	v_or_b32_e32 v28, 48, v36
	v_mov_b32_e32 v29, v37
	v_lshlrev_b64 v[28:29], 13, v[28:29]
	v_lshl_add_u64 v[28:29], v[2:3], 0, v[28:29]
	v_or_b32_e32 v36, 56, v36
	global_load_dwordx4 v[28:31], v[28:29], off
	v_lshlrev_b64 v[32:33], 13, v[36:37]
	v_lshl_add_u64 v[2:3], v[2:3], 0, v[32:33]
	global_load_dwordx4 v[92:95], v[2:3], off
	s_mov_b32 s7, s1
	v_lshl_add_u64 v[2:3], s[6:7], 1, v[40:41]
	v_lshlrev_b32_e32 v36, 9, v90
	v_lshl_add_u64 v[32:33], v[2:3], 0, v[36:37]
	v_lshlrev_b32_e32 v36, 9, v89
	s_mov_b64 s[6:7], 0
	s_waitcnt vmcnt(0)
	ds_write2_b32 v74, v4, v5 offset1:1
	ds_write2_b32 v74, v6, v7 offset0:2 offset1:3
	s_waitcnt vmcnt(6)
	ds_write2_b32 v75, v8, v9 offset1:1
	ds_write2_b32 v76, v10, v11 offset1:1
	s_waitcnt vmcnt(5)
	ds_write2_b32 v77, v12, v13 offset1:1
	ds_write2_b32 v78, v14, v15 offset1:1
	s_waitcnt vmcnt(4)
	ds_write2_b32 v79, v16, v17 offset1:1
	ds_write2_b32 v80, v18, v19 offset1:1
	s_waitcnt vmcnt(3)
	ds_write2_b32 v81, v20, v21 offset1:1
	ds_write2_b32 v82, v22, v23 offset1:1
	s_waitcnt vmcnt(2)
	ds_write2_b32 v83, v24, v25 offset1:1
	ds_write2_b32 v84, v26, v27 offset1:1
	s_waitcnt vmcnt(1)
	ds_write2_b32 v85, v28, v29 offset1:1
	ds_write2_b32 v86, v30, v31 offset1:1
	s_waitcnt vmcnt(0)
	ds_write2_b32 v87, v92, v93 offset1:1
	ds_write2_b32 v88, v94, v95 offset1:1
	s_waitcnt lgkmcnt(0)
	ds_read_b32 v4, v73
	ds_read_b32 v5, v73 offset:132
	ds_read_b32 v6, v73 offset:264
	ds_read_b32 v7, v73 offset:396
	ds_read_b32 v8, v73 offset:528
	ds_read_b32 v9, v73 offset:660
	ds_read_b32 v10, v73 offset:792
	ds_read_b32 v11, v73 offset:924
	s_waitcnt lgkmcnt(0)
	v_bfe_u32 v12, v4, 16, 1
	s_waitcnt lgkmcnt(5)
	v_bfe_u32 v14, v6, 16, 1
	s_waitcnt lgkmcnt(3)
	v_bfe_u32 v16, v8, 16, 1
	s_waitcnt lgkmcnt(1)
	v_bfe_u32 v18, v10, 16, 1
	v_bfe_u32 v13, v5, 16, 1
	v_bfe_u32 v15, v7, 16, 1
	v_bfe_u32 v17, v9, 16, 1
	s_waitcnt lgkmcnt(0)
	v_bfe_u32 v19, v11, 16, 1
	v_add3_u32 v4, v4, v12, s35
	v_add3_u32 v6, v6, v14, s35
	v_add3_u32 v8, v8, v16, s35
	v_add3_u32 v10, v10, v18, s35
	v_add3_u32 v5, v5, v13, s35
	v_add3_u32 v7, v7, v15, s35
	v_add3_u32 v9, v9, v17, s35
	v_add3_u32 v11, v11, v19, s35
	v_lshrrev_b32_e32 v4, 16, v4
	v_lshrrev_b32_e32 v6, 16, v6
	v_lshrrev_b32_e32 v8, 16, v8
	v_lshrrev_b32_e32 v10, 16, v10
	v_and_or_b32 v4, v5, s36, v4
	v_and_or_b32 v5, v7, s36, v6
	v_and_or_b32 v6, v9, s36, v8
	v_and_or_b32 v7, v11, s36, v10
	global_store_dwordx4 v[32:33], v[4:7], off
	ds_read_b32 v4, v73 offset:32
	ds_read_b32 v5, v73 offset:164
	ds_read_b32 v6, v73 offset:296
	ds_read_b32 v7, v73 offset:428
	ds_read_b32 v8, v73 offset:560
	ds_read_b32 v9, v73 offset:692
	ds_read_b32 v10, v73 offset:824
	ds_read_b32 v11, v73 offset:956
	s_waitcnt lgkmcnt(0)
	v_bfe_u32 v12, v4, 16, 1
	v_add3_u32 v4, v4, v12, s35
	v_bfe_u32 v12, v5, 16, 1
	v_lshrrev_b32_e32 v4, 16, v4
	v_add3_u32 v5, v5, v12, s35
	v_and_or_b32 v4, v5, s36, v4
	v_bfe_u32 v5, v6, 16, 1
	v_add3_u32 v5, v6, v5, s35
	v_bfe_u32 v6, v7, 16, 1
	v_lshrrev_b32_e32 v5, 16, v5
	v_add3_u32 v6, v7, v6, s35
	v_and_or_b32 v5, v6, s36, v5
	v_bfe_u32 v6, v8, 16, 1
	v_add3_u32 v6, v8, v6, s35
	v_bfe_u32 v7, v9, 16, 1
	v_lshrrev_b32_e32 v6, 16, v6
	v_add3_u32 v7, v9, v7, s35
	v_and_or_b32 v6, v7, s36, v6
	v_bfe_u32 v7, v10, 16, 1
	v_add3_u32 v7, v10, v7, s35
	v_bfe_u32 v8, v11, 16, 1
	v_lshrrev_b32_e32 v7, 16, v7
	v_add3_u32 v8, v11, v8, s35
	v_and_or_b32 v7, v8, s36, v7
	v_lshl_add_u64 v[8:9], v[2:3], 0, v[36:37]
	global_store_dwordx4 v[8:9], v[4:7], off
	ds_read_b32 v4, v73 offset:64
	ds_read_b32 v5, v73 offset:196
	ds_read_b32 v6, v73 offset:328
	ds_read_b32 v7, v73 offset:460
	ds_read_b32 v8, v73 offset:592
	ds_read_b32 v9, v73 offset:724
	ds_read_b32 v10, v73 offset:856
	ds_read_b32 v11, v73 offset:988
	s_waitcnt lgkmcnt(0)
	v_bfe_u32 v12, v4, 16, 1
	v_add3_u32 v4, v4, v12, s35
	v_bfe_u32 v12, v5, 16, 1
	v_lshrrev_b32_e32 v4, 16, v4
	v_add3_u32 v5, v5, v12, s35
	v_and_or_b32 v4, v5, s36, v4
	v_bfe_u32 v5, v6, 16, 1
	v_add3_u32 v5, v6, v5, s35
	v_bfe_u32 v6, v7, 16, 1
	v_lshrrev_b32_e32 v5, 16, v5
	v_add3_u32 v6, v7, v6, s35
	v_and_or_b32 v5, v6, s36, v5
	v_bfe_u32 v6, v8, 16, 1
	v_add3_u32 v6, v8, v6, s35
	v_bfe_u32 v7, v9, 16, 1
	v_lshrrev_b32_e32 v6, 16, v6
	v_add3_u32 v7, v9, v7, s35
	v_and_or_b32 v6, v7, s36, v6
	v_bfe_u32 v7, v10, 16, 1
	v_add3_u32 v7, v10, v7, s35
	v_bfe_u32 v8, v11, 16, 1
	v_lshrrev_b32_e32 v7, 16, v7
	v_add3_u32 v8, v11, v8, s35
	v_lshlrev_b32_e32 v36, 9, v69
	v_and_or_b32 v7, v8, s36, v7
	v_lshl_add_u64 v[8:9], v[2:3], 0, v[36:37]
	global_store_dwordx4 v[8:9], v[4:7], off
	ds_read_b32 v4, v73 offset:96
	ds_read_b32 v5, v73 offset:228
	ds_read_b32 v6, v73 offset:360
	ds_read_b32 v7, v73 offset:492
	ds_read_b32 v8, v73 offset:624
	ds_read_b32 v9, v73 offset:756
	ds_read_b32 v10, v73 offset:888
	ds_read_b32 v11, v73 offset:1020
	s_waitcnt lgkmcnt(0)
	v_bfe_u32 v12, v4, 16, 1
	v_add3_u32 v4, v4, v12, s35
	v_bfe_u32 v12, v5, 16, 1
	v_lshrrev_b32_e32 v4, 16, v4
	v_add3_u32 v5, v5, v12, s35
	v_and_or_b32 v4, v5, s36, v4
	v_bfe_u32 v5, v6, 16, 1
	v_add3_u32 v5, v6, v5, s35
	v_bfe_u32 v6, v7, 16, 1
	v_lshrrev_b32_e32 v5, 16, v5
	v_add3_u32 v6, v7, v6, s35
	v_and_or_b32 v5, v6, s36, v5
	v_bfe_u32 v6, v8, 16, 1
	v_add3_u32 v6, v8, v6, s35
	v_bfe_u32 v7, v9, 16, 1
	v_lshrrev_b32_e32 v6, 16, v6
	v_add3_u32 v7, v9, v7, s35
	v_and_or_b32 v6, v7, s36, v6
	v_bfe_u32 v7, v10, 16, 1
	v_add3_u32 v7, v10, v7, s35
	v_bfe_u32 v8, v11, 16, 1
	v_lshrrev_b32_e32 v7, 16, v7
	v_add3_u32 v8, v11, v8, s35
	v_lshlrev_b32_e32 v36, 9, v68
	v_and_or_b32 v7, v8, s36, v7
	v_lshl_add_u64 v[2:3], v[2:3], 0, v[36:37]
	global_store_dwordx4 v[2:3], v[4:7], off
	s_waitcnt lgkmcnt(0)

.LBB0_24:
	s_waitcnt vmcnt(0)
	ds_write2_b32 v74, v6, v7 offset1:1
	ds_write2_b32 v74, v8, v9 offset0:2 offset1:3
	ds_write2_b32 v75, v2, v3 offset1:1
	ds_write2_b32 v76, v4, v5 offset1:1
	ds_write2_b32 v77, v14, v15 offset1:1
	ds_write2_b32 v78, v16, v17 offset1:1
	ds_write2_b32 v79, v10, v11 offset1:1
	ds_write2_b32 v80, v12, v13 offset1:1
	ds_write2_b32 v81, v22, v23 offset1:1
	ds_write2_b32 v82, v24, v25 offset1:1
	ds_write2_b32 v83, v18, v19 offset1:1
	ds_write2_b32 v84, v20, v21 offset1:1
	ds_write2_b32 v85, v30, v31 offset1:1
	ds_write2_b32 v86, v32, v33 offset1:1
	ds_write2_b32 v87, v26, v27 offset1:1
	ds_write2_b32 v88, v28, v29 offset1:1
	s_waitcnt lgkmcnt(0)
	ds_read_b32 v2, v73
	ds_read_b32 v3, v73 offset:132
	ds_read_b32 v4, v73 offset:264
	ds_read_b32 v5, v73 offset:396
	ds_read_b32 v8, v73 offset:528
	ds_read_b32 v9, v73 offset:660
	ds_read_b32 v10, v73 offset:792
	ds_read_b32 v11, v73 offset:924
	s_waitcnt lgkmcnt(0)
	v_bfe_u32 v12, v2, 16, 1
	v_add3_u32 v2, v2, v12, s35
	v_bfe_u32 v12, v3, 16, 1
	v_lshrrev_b32_e32 v2, 16, v2
	v_add3_u32 v3, v3, v12, s35
	v_and_or_b32 v2, v3, s36, v2
	v_bfe_u32 v3, v4, 16, 1
	v_add3_u32 v3, v4, v3, s35
	v_bfe_u32 v4, v5, 16, 1
	v_lshrrev_b32_e32 v3, 16, v3
	v_add3_u32 v4, v5, v4, s35
	v_and_or_b32 v3, v4, s36, v3
	v_bfe_u32 v4, v8, 16, 1
	v_add3_u32 v4, v8, v4, s35
	v_bfe_u32 v5, v9, 16, 1
	v_lshrrev_b32_e32 v4, 16, v4
	v_add3_u32 v5, v9, v5, s35
	v_and_or_b32 v4, v5, s36, v4
	v_bfe_u32 v5, v10, 16, 1
	s_mov_b32 s7, s1
	v_add3_u32 v5, v10, v5, s35
	v_bfe_u32 v8, v11, 16, 1
	v_lshl_add_u64 v[6:7], s[6:7], 1, v[44:45]
	v_lshrrev_b32_e32 v5, 16, v5
	v_add3_u32 v8, v11, v8, s35
	v_lshlrev_b32_e32 v36, 12, v90
	v_and_or_b32 v5, v8, s36, v5
	v_lshl_add_u64 v[8:9], v[6:7], 0, v[36:37]
	global_store_dwordx4 v[8:9], v[2:5], off
	ds_read_b32 v2, v73 offset:32
	ds_read_b32 v3, v73 offset:164
	ds_read_b32 v4, v73 offset:296
	ds_read_b32 v5, v73 offset:428
	ds_read_b32 v8, v73 offset:560
	ds_read_b32 v9, v73 offset:692
	ds_read_b32 v10, v73 offset:824
	ds_read_b32 v11, v73 offset:956
	s_waitcnt lgkmcnt(0)
	v_bfe_u32 v12, v2, 16, 1
	v_add3_u32 v2, v2, v12, s35
	v_bfe_u32 v12, v3, 16, 1
	v_lshrrev_b32_e32 v2, 16, v2
	v_add3_u32 v3, v3, v12, s35
	v_and_or_b32 v2, v3, s36, v2
	v_bfe_u32 v3, v4, 16, 1
	v_add3_u32 v3, v4, v3, s35
	v_bfe_u32 v4, v5, 16, 1
	v_lshrrev_b32_e32 v3, 16, v3
	v_add3_u32 v4, v5, v4, s35
	v_and_or_b32 v3, v4, s36, v3
	v_bfe_u32 v4, v8, 16, 1
	v_add3_u32 v4, v8, v4, s35
	v_bfe_u32 v5, v9, 16, 1
	v_lshrrev_b32_e32 v4, 16, v4
	v_add3_u32 v5, v9, v5, s35
	v_and_or_b32 v4, v5, s36, v4
	v_bfe_u32 v5, v10, 16, 1
	v_add3_u32 v5, v10, v5, s35
	v_bfe_u32 v8, v11, 16, 1
	v_lshrrev_b32_e32 v5, 16, v5
	v_add3_u32 v8, v11, v8, s35
	v_lshlrev_b32_e32 v36, 12, v89
	v_and_or_b32 v5, v8, s36, v5
	v_lshl_add_u64 v[8:9], v[6:7], 0, v[36:37]
	global_store_dwordx4 v[8:9], v[2:5], off
	ds_read_b32 v2, v73 offset:64
	ds_read_b32 v3, v73 offset:196
	ds_read_b32 v4, v73 offset:328
	ds_read_b32 v5, v73 offset:460
	ds_read_b32 v8, v73 offset:592
	ds_read_b32 v9, v73 offset:724
	ds_read_b32 v10, v73 offset:856
	ds_read_b32 v11, v73 offset:988
	s_waitcnt lgkmcnt(0)
	v_bfe_u32 v12, v2, 16, 1
	v_add3_u32 v2, v2, v12, s35
	v_bfe_u32 v12, v3, 16, 1
	v_lshrrev_b32_e32 v2, 16, v2
	v_add3_u32 v3, v3, v12, s35
	v_and_or_b32 v2, v3, s36, v2
	v_bfe_u32 v3, v4, 16, 1
	v_add3_u32 v3, v4, v3, s35
	v_bfe_u32 v4, v5, 16, 1
	v_lshrrev_b32_e32 v3, 16, v3
	v_add3_u32 v4, v5, v4, s35
	v_and_or_b32 v3, v4, s36, v3
	v_bfe_u32 v4, v8, 16, 1
	v_add3_u32 v4, v8, v4, s35
	v_bfe_u32 v5, v9, 16, 1
	v_lshrrev_b32_e32 v4, 16, v4
	v_add3_u32 v5, v9, v5, s35
	v_and_or_b32 v4, v5, s36, v4
	v_bfe_u32 v5, v10, 16, 1
	v_add3_u32 v5, v10, v5, s35
	v_bfe_u32 v8, v11, 16, 1
	v_lshrrev_b32_e32 v5, 16, v5
	v_add3_u32 v8, v11, v8, s35
	v_lshlrev_b32_e32 v36, 12, v69
	v_and_or_b32 v5, v8, s36, v5
	v_lshl_add_u64 v[8:9], v[6:7], 0, v[36:37]
	global_store_dwordx4 v[8:9], v[2:5], off
	ds_read_b32 v2, v73 offset:96
	ds_read_b32 v3, v73 offset:228
	ds_read_b32 v4, v73 offset:360
	ds_read_b32 v5, v73 offset:492
	ds_read_b32 v8, v73 offset:624
	ds_read_b32 v9, v73 offset:756
	ds_read_b32 v10, v73 offset:888
	ds_read_b32 v11, v73 offset:1020
	s_waitcnt lgkmcnt(0)
	v_bfe_u32 v12, v2, 16, 1
	v_add3_u32 v2, v2, v12, s35
	v_bfe_u32 v12, v3, 16, 1
	v_lshrrev_b32_e32 v2, 16, v2
	v_add3_u32 v3, v3, v12, s35
	v_and_or_b32 v2, v3, s36, v2
	v_bfe_u32 v3, v4, 16, 1
	v_add3_u32 v3, v4, v3, s35
	v_bfe_u32 v4, v5, 16, 1
	v_lshrrev_b32_e32 v3, 16, v3
	v_add3_u32 v4, v5, v4, s35
	v_and_or_b32 v3, v4, s36, v3
	v_bfe_u32 v4, v8, 16, 1
	v_add3_u32 v4, v8, v4, s35
	v_bfe_u32 v5, v9, 16, 1
	v_lshrrev_b32_e32 v4, 16, v4
	v_add3_u32 v5, v9, v5, s35
	v_and_or_b32 v4, v5, s36, v4
	v_bfe_u32 v5, v10, 16, 1
	v_add3_u32 v5, v10, v5, s35
	v_bfe_u32 v8, v11, 16, 1
	v_lshrrev_b32_e32 v5, 16, v5
	v_add3_u32 v8, v11, v8, s35
	v_lshlrev_b32_e32 v36, 12, v68
	v_and_or_b32 v5, v8, s36, v5
	v_lshl_add_u64 v[6:7], v[6:7], 0, v[36:37]
	global_store_dwordx4 v[6:7], v[2:5], off
	s_waitcnt lgkmcnt(0)

.LBB0_26:
	s_andn2_b64 vcc, exec, s[6:7]
	s_cbranch_vccnz .LBB0_28
	s_and_b32 s0, s45, 0x7fc0
	s_add_i32 s6, s0, 0xffffb500
	s_and_b32 s18, s22, 0x7e0
	v_or_b32_e32 v36, s6, v35
	s_lshl_b32 s0, s18, 2
	v_or_b32_e32 v4, 8, v36
	v_mov_b32_e32 v5, v37
	v_or_b32_e32 v10, 16, v36
	v_mov_b32_e32 v11, v37
	v_or_b32_e32 v12, 24, v36
	v_mov_b32_e32 v13, v37
	v_or_b32_e32 v18, 32, v36
	v_mov_b32_e32 v19, v37
	v_or_b32_e32 v20, 40, v36
	v_mov_b32_e32 v21, v37
	v_lshl_add_u64 v[30:31], v[46:47], 0, s[0:1]
	v_lshlrev_b64 v[2:3], 13, v[36:37]
	v_lshlrev_b64 v[4:5], 13, v[4:5]
	v_lshlrev_b64 v[10:11], 13, v[10:11]
	v_lshlrev_b64 v[12:13], 13, v[12:13]
	v_lshlrev_b64 v[18:19], 13, v[18:19]
	v_lshlrev_b64 v[20:21], 13, v[20:21]
	v_lshl_add_u64 v[2:3], v[30:31], 0, v[2:3]
	v_lshl_add_u64 v[6:7], v[30:31], 0, v[4:5]
	v_lshl_add_u64 v[10:11], v[30:31], 0, v[10:11]
	v_lshl_add_u64 v[14:15], v[30:31], 0, v[12:13]
	v_lshl_add_u64 v[18:19], v[30:31], 0, v[18:19]
	v_lshl_add_u64 v[22:23], v[30:31], 0, v[20:21]
	global_load_dwordx4 v[2:5], v[2:3], off
	s_nop 0
	global_load_dwordx4 v[6:9], v[6:7], off
	s_nop 0
	global_load_dwordx4 v[10:13], v[10:11], off
	s_nop 0
	global_load_dwordx4 v[14:17], v[14:15], off
	s_nop 0
	global_load_dwordx4 v[18:21], v[18:19], off
	s_nop 0
	global_load_dwordx4 v[22:25], v[22:23], off
	v_or_b32_e32 v26, 48, v36
	v_mov_b32_e32 v27, v37
	v_lshlrev_b64 v[26:27], 13, v[26:27]
	v_lshl_add_u64 v[26:27], v[30:31], 0, v[26:27]
	v_or_b32_e32 v36, 56, v36
	global_load_dwordx4 v[26:29], v[26:27], off
	v_lshlrev_b64 v[32:33], 13, v[36:37]
	v_lshl_add_u64 v[30:31], v[30:31], 0, v[32:33]
	global_load_dwordx4 v[30:33], v[30:31], off
	v_or_b32_e32 v36, s18, v35
	s_mov_b32 s7, s1
	v_mul_u32_u24_e32 v36, 0x1600, v36
	v_lshl_add_u64 v[68:69], s[6:7], 1, v[48:49]
	v_lshlrev_b32_e32 v36, 1, v36
	s_waitcnt vmcnt(0)
	ds_write2_b32 v74, v2, v3 offset1:1
	ds_write2_b32 v74, v4, v5 offset0:2 offset1:3
	ds_write2_b32 v75, v6, v7 offset1:1
	ds_write2_b32 v76, v8, v9 offset1:1
	ds_write2_b32 v77, v10, v11 offset1:1
	ds_write2_b32 v78, v12, v13 offset1:1
	ds_write2_b32 v79, v14, v15 offset1:1
	ds_write2_b32 v80, v16, v17 offset1:1
	ds_write2_b32 v81, v18, v19 offset1:1
	ds_write2_b32 v82, v20, v21 offset1:1
	ds_write2_b32 v83, v22, v23 offset1:1
	ds_write2_b32 v84, v24, v25 offset1:1
	ds_write2_b32 v85, v26, v27 offset1:1
	ds_write2_b32 v86, v28, v29 offset1:1
	ds_write2_b32 v87, v30, v31 offset1:1
	ds_write2_b32 v88, v32, v33 offset1:1
	s_waitcnt lgkmcnt(0)
	ds_read_b32 v2, v73
	ds_read_b32 v3, v73 offset:132
	ds_read_b32 v4, v73 offset:264
	ds_read_b32 v5, v73 offset:396
	ds_read_b32 v6, v73 offset:528
	ds_read_b32 v7, v73 offset:660
	ds_read_b32 v8, v73 offset:792
	ds_read_b32 v9, v73 offset:924
	s_waitcnt lgkmcnt(0)
	v_bfe_u32 v10, v2, 16, 1
	v_bfe_u32 v12, v4, 16, 1
	v_bfe_u32 v14, v6, 16, 1
	v_bfe_u32 v16, v8, 16, 1
	v_bfe_u32 v11, v3, 16, 1
	v_bfe_u32 v13, v5, 16, 1
	v_bfe_u32 v15, v7, 16, 1
	v_bfe_u32 v17, v9, 16, 1
	v_add3_u32 v2, v2, v10, s35
	v_add3_u32 v4, v4, v12, s35
	v_add3_u32 v6, v6, v14, s35
	v_add3_u32 v8, v8, v16, s35
	v_add3_u32 v3, v3, v11, s35
	v_add3_u32 v5, v5, v13, s35
	v_add3_u32 v7, v7, v15, s35
	v_add3_u32 v9, v9, v17, s35
	v_lshrrev_b32_e32 v2, 16, v2
	v_lshrrev_b32_e32 v4, 16, v4
	v_lshrrev_b32_e32 v6, 16, v6
	v_lshrrev_b32_e32 v8, 16, v8
	v_and_or_b32 v2, v3, s36, v2
	v_and_or_b32 v3, v5, s36, v4
	v_and_or_b32 v4, v7, s36, v6
	v_and_or_b32 v5, v9, s36, v8
	v_lshl_add_u64 v[6:7], v[68:69], 0, v[36:37]
	global_store_dwordx4 v[6:7], v[2:5], off
	ds_read_b32 v2, v73 offset:32
	ds_read_b32 v3, v73 offset:164
	ds_read_b32 v4, v73 offset:296
	ds_read_b32 v5, v73 offset:428
	ds_read_b32 v6, v73 offset:560
	ds_read_b32 v7, v73 offset:692
	ds_read_b32 v8, v73 offset:824
	ds_read_b32 v9, v73 offset:956
	s_waitcnt lgkmcnt(0)
	v_bfe_u32 v10, v2, 16, 1
	v_add3_u32 v2, v2, v10, s35
	v_bfe_u32 v10, v3, 16, 1
	v_lshrrev_b32_e32 v2, 16, v2
	v_add3_u32 v3, v3, v10, s35
	v_and_or_b32 v2, v3, s36, v2
	v_bfe_u32 v3, v4, 16, 1
	v_add3_u32 v3, v4, v3, s35
	v_bfe_u32 v4, v5, 16, 1
	v_lshrrev_b32_e32 v3, 16, v3
	v_add3_u32 v4, v5, v4, s35
	v_and_or_b32 v3, v4, s36, v3
	v_bfe_u32 v4, v6, 16, 1
	v_add3_u32 v4, v6, v4, s35
	v_bfe_u32 v5, v7, 16, 1
	v_lshrrev_b32_e32 v4, 16, v4
	v_add3_u32 v5, v7, v5, s35
	v_and_or_b32 v4, v5, s36, v4
	v_bfe_u32 v5, v8, 16, 1
	v_add3_u32 v5, v8, v5, s35
	v_bfe_u32 v6, v9, 16, 1
	v_lshrrev_b32_e32 v5, 16, v5
	v_add3_u32 v6, v9, v6, s35
	v_and_or_b32 v5, v6, s36, v5
	v_or_b32_e32 v6, s18, v70
	v_mul_u32_u24_e32 v6, 0x1600, v6
	v_lshlrev_b32_e32 v36, 1, v6
	v_lshl_add_u64 v[6:7], v[68:69], 0, v[36:37]
	global_store_dwordx4 v[6:7], v[2:5], off
	ds_read_b32 v2, v73 offset:64
	ds_read_b32 v3, v73 offset:196
	ds_read_b32 v4, v73 offset:328
	ds_read_b32 v5, v73 offset:460
	ds_read_b32 v6, v73 offset:592
	ds_read_b32 v7, v73 offset:724
	ds_read_b32 v8, v73 offset:856
	ds_read_b32 v9, v73 offset:988
	s_waitcnt lgkmcnt(0)
	v_bfe_u32 v10, v2, 16, 1
	v_add3_u32 v2, v2, v10, s35
	v_bfe_u32 v10, v3, 16, 1
	v_lshrrev_b32_e32 v2, 16, v2
	v_add3_u32 v3, v3, v10, s35
	v_and_or_b32 v2, v3, s36, v2
	v_bfe_u32 v3, v4, 16, 1
	v_add3_u32 v3, v4, v3, s35
	v_bfe_u32 v4, v5, 16, 1
	v_lshrrev_b32_e32 v3, 16, v3
	v_add3_u32 v4, v5, v4, s35
	v_and_or_b32 v3, v4, s36, v3
	v_bfe_u32 v4, v6, 16, 1
	v_add3_u32 v4, v6, v4, s35
	v_bfe_u32 v5, v7, 16, 1
	v_lshrrev_b32_e32 v4, 16, v4
	v_add3_u32 v5, v7, v5, s35
	v_and_or_b32 v4, v5, s36, v4
	v_bfe_u32 v5, v8, 16, 1
	v_add3_u32 v5, v8, v5, s35
	v_bfe_u32 v6, v9, 16, 1
	v_lshrrev_b32_e32 v5, 16, v5
	v_add3_u32 v6, v9, v6, s35
	v_and_or_b32 v5, v6, s36, v5
	v_or_b32_e32 v6, s18, v71
	v_mul_u32_u24_e32 v6, 0x1600, v6
	v_lshlrev_b32_e32 v36, 1, v6
	v_lshl_add_u64 v[6:7], v[68:69], 0, v[36:37]
	global_store_dwordx4 v[6:7], v[2:5], off
	ds_read_b32 v2, v73 offset:96
	ds_read_b32 v3, v73 offset:228
	ds_read_b32 v4, v73 offset:360
	ds_read_b32 v5, v73 offset:492
	ds_read_b32 v6, v73 offset:624
	ds_read_b32 v7, v73 offset:756
	ds_read_b32 v8, v73 offset:888
	ds_read_b32 v9, v73 offset:1020
	s_waitcnt lgkmcnt(0)
	v_bfe_u32 v10, v2, 16, 1
	v_add3_u32 v2, v2, v10, s35
	v_bfe_u32 v10, v3, 16, 1
	v_lshrrev_b32_e32 v2, 16, v2
	v_add3_u32 v3, v3, v10, s35
	v_and_or_b32 v2, v3, s36, v2
	v_bfe_u32 v3, v4, 16, 1
	v_add3_u32 v3, v4, v3, s35
	v_bfe_u32 v4, v5, 16, 1
	v_lshrrev_b32_e32 v3, 16, v3
	v_add3_u32 v4, v5, v4, s35
	v_and_or_b32 v3, v4, s36, v3
	v_bfe_u32 v4, v6, 16, 1
	v_add3_u32 v4, v6, v4, s35
	v_bfe_u32 v5, v7, 16, 1
	v_lshrrev_b32_e32 v4, 16, v4
	v_add3_u32 v5, v7, v5, s35
	v_and_or_b32 v4, v5, s36, v4
	v_bfe_u32 v5, v8, 16, 1
	v_add3_u32 v5, v8, v5, s35
	v_bfe_u32 v6, v9, 16, 1
	v_lshrrev_b32_e32 v5, 16, v5
	v_add3_u32 v6, v9, v6, s35
	v_and_or_b32 v5, v6, s36, v5
	v_or_b32_e32 v6, s18, v72
	v_mul_u32_u24_e32 v6, 0x1600, v6
	v_lshlrev_b32_e32 v36, 1, v6
	v_lshl_add_u64 v[6:7], v[68:69], 0, v[36:37]
	global_store_dwordx4 v[6:7], v[2:5], off
	s_waitcnt lgkmcnt(0)

.LBB0_32:
	s_waitcnt vmcnt(0)
	ds_write2_b32 v74, v2, v3 offset1:1
	ds_write2_b32 v74, v4, v5 offset0:2 offset1:3
	ds_write2_b32 v75, v6, v7 offset1:1
	ds_write2_b32 v76, v8, v9 offset1:1
	ds_write2_b32 v77, v10, v11 offset1:1
	ds_write2_b32 v78, v12, v13 offset1:1
	ds_write2_b32 v79, v14, v15 offset1:1
	ds_write2_b32 v80, v16, v17 offset1:1
	ds_write2_b32 v81, v18, v19 offset1:1
	ds_write2_b32 v82, v20, v21 offset1:1
	ds_write2_b32 v83, v22, v23 offset1:1
	ds_write2_b32 v84, v24, v25 offset1:1
	ds_write2_b32 v85, v26, v27 offset1:1
	ds_write2_b32 v86, v28, v29 offset1:1
	ds_write2_b32 v87, v30, v31 offset1:1
	ds_write2_b32 v88, v32, v33 offset1:1
	s_waitcnt lgkmcnt(0)
	ds_read_b32 v2, v73
	ds_read_b32 v3, v73 offset:132
	ds_read_b32 v4, v73 offset:264
	ds_read_b32 v5, v73 offset:396
	ds_read_b32 v8, v73 offset:528
	ds_read_b32 v9, v73 offset:660
	ds_read_b32 v10, v73 offset:792
	ds_read_b32 v11, v73 offset:924
	s_waitcnt lgkmcnt(0)
	v_bfe_u32 v12, v2, 16, 1
	v_add3_u32 v2, v2, v12, s35
	v_bfe_u32 v12, v3, 16, 1
	v_lshrrev_b32_e32 v2, 16, v2
	v_add3_u32 v3, v3, v12, s35
	v_and_or_b32 v2, v3, s36, v2
	v_bfe_u32 v3, v4, 16, 1
	v_add3_u32 v3, v4, v3, s35
	v_bfe_u32 v4, v5, 16, 1
	v_lshrrev_b32_e32 v3, 16, v3
	v_add3_u32 v4, v5, v4, s35
	v_and_or_b32 v3, v4, s36, v3
	v_bfe_u32 v4, v8, 16, 1
	v_add3_u32 v4, v8, v4, s35
	v_bfe_u32 v5, v9, 16, 1
	v_lshrrev_b32_e32 v4, 16, v4
	v_add3_u32 v5, v9, v5, s35
	v_and_or_b32 v4, v5, s36, v4
	v_bfe_u32 v5, v10, 16, 1
	v_add3_u32 v5, v10, v5, s35
	v_bfe_u32 v8, v11, 16, 1
	s_and_b32 s0, 0xffff, s0
	v_lshrrev_b32_e32 v5, 16, v5
	v_add3_u32 v8, v11, v8, s35
	s_lshl_b32 s0, s0, 1
	v_and_or_b32 v5, v8, s36, v5
	v_or_b32_e32 v8, s6, v35
	v_lshl_add_u64 v[6:7], v[50:51], 0, s[0:1]
	v_lshlrev_b32_e32 v36, 12, v8
	v_lshl_add_u64 v[8:9], v[6:7], 0, v[36:37]
	global_store_dwordx4 v[8:9], v[2:5], off
	ds_read_b32 v2, v73 offset:32
	ds_read_b32 v3, v73 offset:164
	ds_read_b32 v4, v73 offset:296
	ds_read_b32 v5, v73 offset:428
	ds_read_b32 v8, v73 offset:560
	ds_read_b32 v9, v73 offset:692
	ds_read_b32 v10, v73 offset:824
	ds_read_b32 v11, v73 offset:956
	s_waitcnt lgkmcnt(0)
	v_bfe_u32 v12, v2, 16, 1
	v_add3_u32 v2, v2, v12, s35
	v_bfe_u32 v12, v3, 16, 1
	v_lshrrev_b32_e32 v2, 16, v2
	v_add3_u32 v3, v3, v12, s35
	v_and_or_b32 v2, v3, s36, v2
	v_bfe_u32 v3, v4, 16, 1
	v_add3_u32 v3, v4, v3, s35
	v_bfe_u32 v4, v5, 16, 1
	v_lshrrev_b32_e32 v3, 16, v3
	v_add3_u32 v4, v5, v4, s35
	v_and_or_b32 v3, v4, s36, v3
	v_bfe_u32 v4, v8, 16, 1
	v_add3_u32 v4, v8, v4, s35
	v_bfe_u32 v5, v9, 16, 1
	v_lshrrev_b32_e32 v4, 16, v4
	v_add3_u32 v5, v9, v5, s35
	v_and_or_b32 v4, v5, s36, v4
	v_bfe_u32 v5, v10, 16, 1
	v_add3_u32 v5, v10, v5, s35
	v_bfe_u32 v8, v11, 16, 1
	v_lshrrev_b32_e32 v5, 16, v5
	v_add3_u32 v8, v11, v8, s35
	v_and_or_b32 v5, v8, s36, v5
	v_or_b32_e32 v8, s6, v70
	v_lshlrev_b32_e32 v36, 12, v8
	v_lshl_add_u64 v[8:9], v[6:7], 0, v[36:37]
	global_store_dwordx4 v[8:9], v[2:5], off
	ds_read_b32 v2, v73 offset:64
	ds_read_b32 v3, v73 offset:196
	ds_read_b32 v4, v73 offset:328
	ds_read_b32 v5, v73 offset:460
	ds_read_b32 v8, v73 offset:592
	ds_read_b32 v9, v73 offset:724
	ds_read_b32 v10, v73 offset:856
	ds_read_b32 v11, v73 offset:988
	s_waitcnt lgkmcnt(0)
	v_bfe_u32 v12, v2, 16, 1
	v_add3_u32 v2, v2, v12, s35
	v_bfe_u32 v12, v3, 16, 1
	v_lshrrev_b32_e32 v2, 16, v2
	v_add3_u32 v3, v3, v12, s35
	v_and_or_b32 v2, v3, s36, v2
	v_bfe_u32 v3, v4, 16, 1
	v_add3_u32 v3, v4, v3, s35
	v_bfe_u32 v4, v5, 16, 1
	v_lshrrev_b32_e32 v3, 16, v3
	v_add3_u32 v4, v5, v4, s35
	v_and_or_b32 v3, v4, s36, v3
	v_bfe_u32 v4, v8, 16, 1
	v_add3_u32 v4, v8, v4, s35
	v_bfe_u32 v5, v9, 16, 1
	v_lshrrev_b32_e32 v4, 16, v4
	v_add3_u32 v5, v9, v5, s35
	v_and_or_b32 v4, v5, s36, v4
	v_bfe_u32 v5, v10, 16, 1
	v_add3_u32 v5, v10, v5, s35
	v_bfe_u32 v8, v11, 16, 1
	v_lshrrev_b32_e32 v5, 16, v5
	v_add3_u32 v8, v11, v8, s35
	v_and_or_b32 v5, v8, s36, v5
	v_or_b32_e32 v8, s6, v71
	v_lshlrev_b32_e32 v36, 12, v8
	v_lshl_add_u64 v[8:9], v[6:7], 0, v[36:37]
	global_store_dwordx4 v[8:9], v[2:5], off
	ds_read_b32 v2, v73 offset:96
	ds_read_b32 v3, v73 offset:228
	ds_read_b32 v4, v73 offset:360
	ds_read_b32 v5, v73 offset:492
	ds_read_b32 v8, v73 offset:624
	ds_read_b32 v9, v73 offset:756
	ds_read_b32 v10, v73 offset:888
	ds_read_b32 v11, v73 offset:1020
	s_waitcnt lgkmcnt(0)
	v_bfe_u32 v12, v2, 16, 1
	v_add3_u32 v2, v2, v12, s35
	v_bfe_u32 v12, v3, 16, 1
	v_lshrrev_b32_e32 v2, 16, v2
	v_add3_u32 v3, v3, v12, s35
	v_and_or_b32 v2, v3, s36, v2
	v_bfe_u32 v3, v4, 16, 1
	v_add3_u32 v3, v4, v3, s35
	v_bfe_u32 v4, v5, 16, 1
	v_lshrrev_b32_e32 v3, 16, v3
	v_add3_u32 v4, v5, v4, s35
	v_and_or_b32 v3, v4, s36, v3
	v_bfe_u32 v4, v8, 16, 1
	v_add3_u32 v4, v8, v4, s35
	v_bfe_u32 v5, v9, 16, 1
	v_lshrrev_b32_e32 v4, 16, v4
	v_add3_u32 v5, v9, v5, s35
	v_and_or_b32 v4, v5, s36, v4
	v_bfe_u32 v5, v10, 16, 1
	v_add3_u32 v5, v10, v5, s35
	v_bfe_u32 v8, v11, 16, 1
	v_lshrrev_b32_e32 v5, 16, v5
	v_add3_u32 v8, v11, v8, s35
	v_and_or_b32 v5, v8, s36, v5
	v_or_b32_e32 v8, s6, v72
	v_lshlrev_b32_e32 v36, 12, v8
	v_lshl_add_u64 v[6:7], v[6:7], 0, v[36:37]
	global_store_dwordx4 v[6:7], v[2:5], off
	s_waitcnt lgkmcnt(0)

.LBB0_34:
	s_andn2_b64 vcc, exec, s[6:7]
	s_cbranch_vccnz .LBB0_36
	s_and_b32 s0, s45, 0x1fc0
	s_add_i32 s6, s0, 0xffffe900
	s_and_b32 s18, s22, 0x7e0
	v_or_b32_e32 v36, s6, v35
	s_lshl_b32 s0, s18, 2
	v_or_b32_e32 v4, 8, v36
	v_mov_b32_e32 v5, v37
	v_or_b32_e32 v10, 16, v36
	v_mov_b32_e32 v11, v37
	v_or_b32_e32 v12, 24, v36
	v_mov_b32_e32 v13, v37
	v_or_b32_e32 v18, 32, v36
	v_mov_b32_e32 v19, v37
	v_or_b32_e32 v20, 40, v36
	v_mov_b32_e32 v21, v37
	v_lshl_add_u64 v[30:31], v[52:53], 0, s[0:1]
	v_lshlrev_b64 v[2:3], 13, v[36:37]
	v_lshlrev_b64 v[4:5], 13, v[4:5]
	v_lshlrev_b64 v[10:11], 13, v[10:11]
	v_lshlrev_b64 v[12:13], 13, v[12:13]
	v_lshlrev_b64 v[18:19], 13, v[18:19]
	v_lshlrev_b64 v[20:21], 13, v[20:21]
	v_lshl_add_u64 v[2:3], v[30:31], 0, v[2:3]
	v_lshl_add_u64 v[6:7], v[30:31], 0, v[4:5]
	v_lshl_add_u64 v[10:11], v[30:31], 0, v[10:11]
	v_lshl_add_u64 v[14:15], v[30:31], 0, v[12:13]
	v_lshl_add_u64 v[18:19], v[30:31], 0, v[18:19]
	v_lshl_add_u64 v[22:23], v[30:31], 0, v[20:21]
	global_load_dwordx4 v[2:5], v[2:3], off
	s_nop 0
	global_load_dwordx4 v[6:9], v[6:7], off
	s_nop 0
	global_load_dwordx4 v[10:13], v[10:11], off
	s_nop 0
	global_load_dwordx4 v[14:17], v[14:15], off
	s_nop 0
	global_load_dwordx4 v[18:21], v[18:19], off
	s_nop 0
	global_load_dwordx4 v[22:25], v[22:23], off
	v_or_b32_e32 v26, 48, v36
	v_mov_b32_e32 v27, v37
	v_lshlrev_b64 v[26:27], 13, v[26:27]
	v_lshl_add_u64 v[26:27], v[30:31], 0, v[26:27]
	v_or_b32_e32 v36, 56, v36
	global_load_dwordx4 v[26:29], v[26:27], off
	v_lshlrev_b64 v[32:33], 13, v[36:37]
	v_lshl_add_u64 v[30:31], v[30:31], 0, v[32:33]
	global_load_dwordx4 v[30:33], v[30:31], off
	s_mov_b32 s7, s1
	v_or_b32_e32 v36, s18, v35
	v_lshl_add_u64 v[68:69], s[6:7], 1, v[54:55]
	v_lshlrev_b32_e32 v36, 12, v36
	v_lshl_add_u64 v[90:91], v[68:69], 0, v[36:37]
	s_waitcnt vmcnt(0)
	ds_write2_b32 v74, v2, v3 offset1:1
	ds_write2_b32 v74, v4, v5 offset0:2 offset1:3
	ds_write2_b32 v75, v6, v7 offset1:1
	ds_write2_b32 v76, v8, v9 offset1:1
	ds_write2_b32 v77, v10, v11 offset1:1
	ds_write2_b32 v78, v12, v13 offset1:1
	ds_write2_b32 v79, v14, v15 offset1:1
	ds_write2_b32 v80, v16, v17 offset1:1
	ds_write2_b32 v81, v18, v19 offset1:1
	ds_write2_b32 v82, v20, v21 offset1:1
	ds_write2_b32 v83, v22, v23 offset1:1
	ds_write2_b32 v84, v24, v25 offset1:1
	ds_write2_b32 v85, v26, v27 offset1:1
	ds_write2_b32 v86, v28, v29 offset1:1
	ds_write2_b32 v87, v30, v31 offset1:1
	ds_write2_b32 v88, v32, v33 offset1:1
	s_waitcnt lgkmcnt(0)
	ds_read_b32 v2, v73
	ds_read_b32 v3, v73 offset:132
	ds_read_b32 v4, v73 offset:264
	ds_read_b32 v5, v73 offset:396
	ds_read_b32 v6, v73 offset:528
	ds_read_b32 v7, v73 offset:660
	ds_read_b32 v8, v73 offset:792
	ds_read_b32 v9, v73 offset:924
	s_waitcnt lgkmcnt(0)
	v_bfe_u32 v10, v2, 16, 1
	v_bfe_u32 v12, v4, 16, 1
	v_bfe_u32 v14, v6, 16, 1
	v_bfe_u32 v16, v8, 16, 1
	v_bfe_u32 v11, v3, 16, 1
	v_bfe_u32 v13, v5, 16, 1
	v_bfe_u32 v15, v7, 16, 1
	v_bfe_u32 v17, v9, 16, 1
	v_add3_u32 v2, v2, v10, s35
	v_add3_u32 v4, v4, v12, s35
	v_add3_u32 v6, v6, v14, s35
	v_add3_u32 v8, v8, v16, s35
	v_add3_u32 v3, v3, v11, s35
	v_add3_u32 v5, v5, v13, s35
	v_add3_u32 v7, v7, v15, s35
	v_add3_u32 v9, v9, v17, s35
	v_lshrrev_b32_e32 v2, 16, v2
	v_lshrrev_b32_e32 v4, 16, v4
	v_lshrrev_b32_e32 v6, 16, v6
	v_lshrrev_b32_e32 v8, 16, v8
	v_and_or_b32 v2, v3, s36, v2
	v_and_or_b32 v3, v5, s36, v4
	v_and_or_b32 v4, v7, s36, v6
	v_and_or_b32 v5, v9, s36, v8
	global_store_dwordx4 v[90:91], v[2:5], off
	ds_read_b32 v2, v73 offset:32
	ds_read_b32 v3, v73 offset:164
	ds_read_b32 v4, v73 offset:296
	ds_read_b32 v5, v73 offset:428
	ds_read_b32 v6, v73 offset:560
	ds_read_b32 v7, v73 offset:692
	ds_read_b32 v8, v73 offset:824
	ds_read_b32 v9, v73 offset:956
	s_waitcnt lgkmcnt(0)
	v_bfe_u32 v10, v2, 16, 1
	v_add3_u32 v2, v2, v10, s35
	v_bfe_u32 v10, v3, 16, 1
	v_lshrrev_b32_e32 v2, 16, v2
	v_add3_u32 v3, v3, v10, s35
	v_and_or_b32 v2, v3, s36, v2
	v_bfe_u32 v3, v4, 16, 1
	v_add3_u32 v3, v4, v3, s35
	v_bfe_u32 v4, v5, 16, 1
	v_lshrrev_b32_e32 v3, 16, v3
	v_add3_u32 v4, v5, v4, s35
	v_and_or_b32 v3, v4, s36, v3
	v_bfe_u32 v4, v6, 16, 1
	v_add3_u32 v4, v6, v4, s35
	v_bfe_u32 v5, v7, 16, 1
	v_lshrrev_b32_e32 v4, 16, v4
	v_add3_u32 v5, v7, v5, s35
	v_and_or_b32 v4, v5, s36, v4
	v_bfe_u32 v5, v8, 16, 1
	v_add3_u32 v5, v8, v5, s35
	v_bfe_u32 v6, v9, 16, 1
	v_lshrrev_b32_e32 v5, 16, v5
	v_add3_u32 v6, v9, v6, s35
	v_and_or_b32 v5, v6, s36, v5
	v_or_b32_e32 v6, s18, v70
	v_lshlrev_b32_e32 v36, 12, v6
	v_lshl_add_u64 v[6:7], v[68:69], 0, v[36:37]
	global_store_dwordx4 v[6:7], v[2:5], off
	ds_read_b32 v2, v73 offset:64
	ds_read_b32 v3, v73 offset:196
	ds_read_b32 v4, v73 offset:328
	ds_read_b32 v5, v73 offset:460
	ds_read_b32 v6, v73 offset:592
	ds_read_b32 v7, v73 offset:724
	ds_read_b32 v8, v73 offset:856
	ds_read_b32 v9, v73 offset:988
	s_waitcnt lgkmcnt(0)
	v_bfe_u32 v10, v2, 16, 1
	v_add3_u32 v2, v2, v10, s35
	v_bfe_u32 v10, v3, 16, 1
	v_lshrrev_b32_e32 v2, 16, v2
	v_add3_u32 v3, v3, v10, s35
	v_and_or_b32 v2, v3, s36, v2
	v_bfe_u32 v3, v4, 16, 1
	v_add3_u32 v3, v4, v3, s35
	v_bfe_u32 v4, v5, 16, 1
	v_lshrrev_b32_e32 v3, 16, v3
	v_add3_u32 v4, v5, v4, s35
	v_and_or_b32 v3, v4, s36, v3
	v_bfe_u32 v4, v6, 16, 1
	v_add3_u32 v4, v6, v4, s35
	v_bfe_u32 v5, v7, 16, 1
	v_lshrrev_b32_e32 v4, 16, v4
	v_add3_u32 v5, v7, v5, s35
	v_and_or_b32 v4, v5, s36, v4
	v_bfe_u32 v5, v8, 16, 1
	v_add3_u32 v5, v8, v5, s35
	v_bfe_u32 v6, v9, 16, 1
	v_lshrrev_b32_e32 v5, 16, v5
	v_add3_u32 v6, v9, v6, s35
	v_and_or_b32 v5, v6, s36, v5
	v_or_b32_e32 v6, s18, v71
	v_lshlrev_b32_e32 v36, 12, v6
	v_lshl_add_u64 v[6:7], v[68:69], 0, v[36:37]
	global_store_dwordx4 v[6:7], v[2:5], off
	ds_read_b32 v2, v73 offset:96
	ds_read_b32 v3, v73 offset:228
	ds_read_b32 v4, v73 offset:360
	ds_read_b32 v5, v73 offset:492
	ds_read_b32 v6, v73 offset:624
	ds_read_b32 v7, v73 offset:756
	ds_read_b32 v8, v73 offset:888
	ds_read_b32 v9, v73 offset:1020
	s_waitcnt lgkmcnt(0)
	v_bfe_u32 v10, v2, 16, 1
	v_add3_u32 v2, v2, v10, s35
	v_bfe_u32 v10, v3, 16, 1
	v_lshrrev_b32_e32 v2, 16, v2
	v_add3_u32 v3, v3, v10, s35
	v_and_or_b32 v2, v3, s36, v2
	v_bfe_u32 v3, v4, 16, 1
	v_add3_u32 v3, v4, v3, s35
	v_bfe_u32 v4, v5, 16, 1
	v_lshrrev_b32_e32 v3, 16, v3
	v_add3_u32 v4, v5, v4, s35
	v_and_or_b32 v3, v4, s36, v3
	v_bfe_u32 v4, v6, 16, 1
	v_add3_u32 v4, v6, v4, s35
	v_bfe_u32 v5, v7, 16, 1
	v_lshrrev_b32_e32 v4, 16, v4
	v_add3_u32 v5, v7, v5, s35
	v_and_or_b32 v4, v5, s36, v4
	v_bfe_u32 v5, v8, 16, 1
	v_add3_u32 v5, v8, v5, s35
	v_bfe_u32 v6, v9, 16, 1
	v_lshrrev_b32_e32 v5, 16, v5
	v_add3_u32 v6, v9, v6, s35
	v_and_or_b32 v5, v6, s36, v5
	v_or_b32_e32 v6, s18, v72
	v_lshlrev_b32_e32 v36, 12, v6
	v_lshl_add_u64 v[6:7], v[68:69], 0, v[36:37]
	global_store_dwordx4 v[6:7], v[2:5], off
	s_waitcnt lgkmcnt(0)

.LBB0_40:
	s_waitcnt vmcnt(0)
	ds_write2_b32 v74, v6, v7 offset1:1
	ds_write2_b32 v74, v8, v9 offset0:2 offset1:3
	ds_write2_b32 v75, v2, v3 offset1:1
	ds_write2_b32 v76, v4, v5 offset1:1
	ds_write2_b32 v77, v14, v15 offset1:1
	ds_write2_b32 v78, v16, v17 offset1:1
	ds_write2_b32 v79, v10, v11 offset1:1
	ds_write2_b32 v80, v12, v13 offset1:1
	ds_write2_b32 v81, v22, v23 offset1:1
	ds_write2_b32 v82, v24, v25 offset1:1
	ds_write2_b32 v83, v18, v19 offset1:1
	ds_write2_b32 v84, v20, v21 offset1:1
	ds_write2_b32 v85, v30, v31 offset1:1
	ds_write2_b32 v86, v32, v33 offset1:1
	ds_write2_b32 v87, v26, v27 offset1:1
	ds_write2_b32 v88, v28, v29 offset1:1
	s_waitcnt lgkmcnt(0)
	ds_read_b32 v2, v73
	ds_read_b32 v3, v73 offset:132
	ds_read_b32 v4, v73 offset:264
	ds_read_b32 v5, v73 offset:396
	ds_read_b32 v8, v73 offset:528
	ds_read_b32 v9, v73 offset:660
	ds_read_b32 v10, v73 offset:792
	ds_read_b32 v11, v73 offset:924
	s_waitcnt lgkmcnt(0)
	v_bfe_u32 v12, v2, 16, 1
	v_add3_u32 v2, v2, v12, s35
	v_bfe_u32 v12, v3, 16, 1
	v_lshrrev_b32_e32 v2, 16, v2
	v_add3_u32 v3, v3, v12, s35
	v_and_or_b32 v2, v3, s36, v2
	v_bfe_u32 v3, v4, 16, 1
	v_add3_u32 v3, v4, v3, s35
	v_bfe_u32 v4, v5, 16, 1
	v_lshrrev_b32_e32 v3, 16, v3
	v_add3_u32 v4, v5, v4, s35
	v_and_or_b32 v3, v4, s36, v3
	v_bfe_u32 v4, v8, 16, 1
	v_add3_u32 v4, v8, v4, s35
	v_bfe_u32 v5, v9, 16, 1
	v_lshrrev_b32_e32 v4, 16, v4
	v_add3_u32 v5, v9, v5, s35
	v_and_or_b32 v4, v5, s36, v4
	v_bfe_u32 v5, v10, 16, 1
	v_add3_u32 v5, v10, v5, s35
	v_bfe_u32 v8, v11, 16, 1
	s_and_b32 s0, s22, 0x3e0
	v_lshrrev_b32_e32 v5, 16, v5
	v_add3_u32 v8, v11, v8, s35
	s_mov_b32 s7, s1
	v_and_or_b32 v5, v8, s36, v5
	v_or_b32_e32 v8, s0, v35
	v_lshl_add_u64 v[6:7], s[6:7], 1, v[56:57]
	v_lshlrev_b32_e32 v36, 10, v8
	v_lshl_add_u64 v[8:9], v[6:7], 0, v[36:37]
	global_store_dwordx4 v[8:9], v[2:5], off
	ds_read_b32 v2, v73 offset:32
	ds_read_b32 v3, v73 offset:164
	ds_read_b32 v4, v73 offset:296
	ds_read_b32 v5, v73 offset:428
	ds_read_b32 v8, v73 offset:560
	ds_read_b32 v9, v73 offset:692
	ds_read_b32 v10, v73 offset:824
	ds_read_b32 v11, v73 offset:956
	s_waitcnt lgkmcnt(0)
	v_bfe_u32 v12, v2, 16, 1
	v_add3_u32 v2, v2, v12, s35
	v_bfe_u32 v12, v3, 16, 1
	v_lshrrev_b32_e32 v2, 16, v2
	v_add3_u32 v3, v3, v12, s35
	v_and_or_b32 v2, v3, s36, v2
	v_bfe_u32 v3, v4, 16, 1
	v_add3_u32 v3, v4, v3, s35
	v_bfe_u32 v4, v5, 16, 1
	v_lshrrev_b32_e32 v3, 16, v3
	v_add3_u32 v4, v5, v4, s35
	v_and_or_b32 v3, v4, s36, v3
	v_bfe_u32 v4, v8, 16, 1
	v_add3_u32 v4, v8, v4, s35
	v_bfe_u32 v5, v9, 16, 1
	v_lshrrev_b32_e32 v4, 16, v4
	v_add3_u32 v5, v9, v5, s35
	v_and_or_b32 v4, v5, s36, v4
	v_bfe_u32 v5, v10, 16, 1
	v_add3_u32 v5, v10, v5, s35
	v_bfe_u32 v8, v11, 16, 1
	v_lshrrev_b32_e32 v5, 16, v5
	v_add3_u32 v8, v11, v8, s35
	v_and_or_b32 v5, v8, s36, v5
	v_or_b32_e32 v8, s0, v70
	v_lshlrev_b32_e32 v36, 10, v8
	v_lshl_add_u64 v[8:9], v[6:7], 0, v[36:37]
	global_store_dwordx4 v[8:9], v[2:5], off
	ds_read_b32 v2, v73 offset:64
	ds_read_b32 v3, v73 offset:196
	ds_read_b32 v4, v73 offset:328
	ds_read_b32 v5, v73 offset:460
	ds_read_b32 v8, v73 offset:592
	ds_read_b32 v9, v73 offset:724
	ds_read_b32 v10, v73 offset:856
	ds_read_b32 v11, v73 offset:988
	s_waitcnt lgkmcnt(0)
	v_bfe_u32 v12, v2, 16, 1
	v_add3_u32 v2, v2, v12, s35
	v_bfe_u32 v12, v3, 16, 1
	v_lshrrev_b32_e32 v2, 16, v2
	v_add3_u32 v3, v3, v12, s35
	v_and_or_b32 v2, v3, s36, v2
	v_bfe_u32 v3, v4, 16, 1
	v_add3_u32 v3, v4, v3, s35
	v_bfe_u32 v4, v5, 16, 1
	v_lshrrev_b32_e32 v3, 16, v3
	v_add3_u32 v4, v5, v4, s35
	v_and_or_b32 v3, v4, s36, v3
	v_bfe_u32 v4, v8, 16, 1
	v_add3_u32 v4, v8, v4, s35
	v_bfe_u32 v5, v9, 16, 1
	v_lshrrev_b32_e32 v4, 16, v4
	v_add3_u32 v5, v9, v5, s35
	v_and_or_b32 v4, v5, s36, v4
	v_bfe_u32 v5, v10, 16, 1
	v_add3_u32 v5, v10, v5, s35
	v_bfe_u32 v8, v11, 16, 1
	v_lshrrev_b32_e32 v5, 16, v5
	v_add3_u32 v8, v11, v8, s35
	v_and_or_b32 v5, v8, s36, v5
	v_or_b32_e32 v8, s0, v71
	v_lshlrev_b32_e32 v36, 10, v8
	v_lshl_add_u64 v[8:9], v[6:7], 0, v[36:37]
	global_store_dwordx4 v[8:9], v[2:5], off
	ds_read_b32 v2, v73 offset:96
	ds_read_b32 v3, v73 offset:228
	ds_read_b32 v4, v73 offset:360
	ds_read_b32 v5, v73 offset:492
	ds_read_b32 v8, v73 offset:624
	ds_read_b32 v9, v73 offset:756
	ds_read_b32 v10, v73 offset:888
	ds_read_b32 v11, v73 offset:1020
	s_waitcnt lgkmcnt(0)
	v_bfe_u32 v12, v2, 16, 1
	v_add3_u32 v2, v2, v12, s35
	v_bfe_u32 v12, v3, 16, 1
	v_lshrrev_b32_e32 v2, 16, v2
	v_add3_u32 v3, v3, v12, s35
	v_and_or_b32 v2, v3, s36, v2
	v_bfe_u32 v3, v4, 16, 1
	v_add3_u32 v3, v4, v3, s35
	v_bfe_u32 v4, v5, 16, 1
	v_lshrrev_b32_e32 v3, 16, v3
	v_add3_u32 v4, v5, v4, s35
	v_and_or_b32 v3, v4, s36, v3
	v_bfe_u32 v4, v8, 16, 1
	v_add3_u32 v4, v8, v4, s35
	v_bfe_u32 v5, v9, 16, 1
	v_lshrrev_b32_e32 v4, 16, v4
	v_add3_u32 v5, v9, v5, s35
	v_and_or_b32 v4, v5, s36, v4
	v_bfe_u32 v5, v10, 16, 1
	v_add3_u32 v5, v10, v5, s35
	v_bfe_u32 v8, v11, 16, 1
	v_lshrrev_b32_e32 v5, 16, v5
	v_add3_u32 v8, v11, v8, s35
	v_and_or_b32 v5, v8, s36, v5
	v_or_b32_e32 v8, s0, v72
	v_lshlrev_b32_e32 v36, 10, v8
	v_lshl_add_u64 v[6:7], v[6:7], 0, v[36:37]
	global_store_dwordx4 v[6:7], v[2:5], off
	s_waitcnt lgkmcnt(0)

.LBB0_45:
	s_waitcnt vmcnt(0)
	ds_write2_b32 v74, v6, v7 offset1:1
	ds_write2_b32 v74, v8, v9 offset0:2 offset1:3
	ds_write2_b32 v75, v2, v3 offset1:1
	ds_write2_b32 v76, v4, v5 offset1:1
	ds_write2_b32 v77, v14, v15 offset1:1
	ds_write2_b32 v78, v16, v17 offset1:1
	ds_write2_b32 v79, v10, v11 offset1:1
	ds_write2_b32 v80, v12, v13 offset1:1
	ds_write2_b32 v81, v22, v23 offset1:1
	ds_write2_b32 v82, v24, v25 offset1:1
	ds_write2_b32 v83, v18, v19 offset1:1
	ds_write2_b32 v84, v20, v21 offset1:1
	ds_write2_b32 v85, v30, v31 offset1:1
	ds_write2_b32 v86, v32, v33 offset1:1
	ds_write2_b32 v87, v26, v27 offset1:1
	ds_write2_b32 v88, v28, v29 offset1:1
	s_waitcnt lgkmcnt(0)
	ds_read_b32 v2, v73
	ds_read_b32 v3, v73 offset:132
	ds_read_b32 v4, v73 offset:264
	ds_read_b32 v5, v73 offset:396
	ds_read_b32 v8, v73 offset:528
	ds_read_b32 v9, v73 offset:660
	ds_read_b32 v10, v73 offset:792
	ds_read_b32 v11, v73 offset:924
	s_waitcnt lgkmcnt(0)
	v_bfe_u32 v12, v2, 16, 1
	v_add3_u32 v2, v2, v12, s35
	v_bfe_u32 v12, v3, 16, 1
	v_lshrrev_b32_e32 v2, 16, v2
	v_add3_u32 v3, v3, v12, s35
	v_and_or_b32 v2, v3, s36, v2
	v_bfe_u32 v3, v4, 16, 1
	v_add3_u32 v3, v4, v3, s35
	v_bfe_u32 v4, v5, 16, 1
	v_lshrrev_b32_e32 v3, 16, v3
	v_add3_u32 v4, v5, v4, s35
	v_and_or_b32 v3, v4, s36, v3
	v_bfe_u32 v4, v8, 16, 1
	v_add3_u32 v4, v8, v4, s35
	v_bfe_u32 v5, v9, 16, 1
	v_lshrrev_b32_e32 v4, 16, v4
	v_add3_u32 v5, v9, v5, s35
	v_and_or_b32 v4, v5, s36, v4
	v_bfe_u32 v5, v10, 16, 1
	v_add3_u32 v5, v10, v5, s35
	v_bfe_u32 v8, v11, 16, 1
	s_and_b32 s0, s22, 0x3e0
	v_lshrrev_b32_e32 v5, 16, v5
	v_add3_u32 v8, v11, v8, s35
	s_mov_b32 s7, s1
	v_and_or_b32 v5, v8, s36, v5
	v_or_b32_e32 v8, s0, v35
	v_lshl_add_u64 v[6:7], s[6:7], 1, v[60:61]
	v_lshlrev_b32_e32 v36, 10, v8
	v_lshl_add_u64 v[8:9], v[6:7], 0, v[36:37]
	global_store_dwordx4 v[8:9], v[2:5], off
	ds_read_b32 v2, v73 offset:32
	ds_read_b32 v3, v73 offset:164
	ds_read_b32 v4, v73 offset:296
	ds_read_b32 v5, v73 offset:428
	ds_read_b32 v8, v73 offset:560
	ds_read_b32 v9, v73 offset:692
	ds_read_b32 v10, v73 offset:824
	ds_read_b32 v11, v73 offset:956
	s_waitcnt lgkmcnt(0)
	v_bfe_u32 v12, v2, 16, 1
	v_add3_u32 v2, v2, v12, s35
	v_bfe_u32 v12, v3, 16, 1
	v_lshrrev_b32_e32 v2, 16, v2
	v_add3_u32 v3, v3, v12, s35
	v_and_or_b32 v2, v3, s36, v2
	v_bfe_u32 v3, v4, 16, 1
	v_add3_u32 v3, v4, v3, s35
	v_bfe_u32 v4, v5, 16, 1
	v_lshrrev_b32_e32 v3, 16, v3
	v_add3_u32 v4, v5, v4, s35
	v_and_or_b32 v3, v4, s36, v3
	v_bfe_u32 v4, v8, 16, 1
	v_add3_u32 v4, v8, v4, s35
	v_bfe_u32 v5, v9, 16, 1
	v_lshrrev_b32_e32 v4, 16, v4
	v_add3_u32 v5, v9, v5, s35
	v_and_or_b32 v4, v5, s36, v4
	v_bfe_u32 v5, v10, 16, 1
	v_add3_u32 v5, v10, v5, s35
	v_bfe_u32 v8, v11, 16, 1
	v_lshrrev_b32_e32 v5, 16, v5
	v_add3_u32 v8, v11, v8, s35
	v_and_or_b32 v5, v8, s36, v5
	v_or_b32_e32 v8, s0, v70
	v_lshlrev_b32_e32 v36, 10, v8
	v_lshl_add_u64 v[8:9], v[6:7], 0, v[36:37]
	global_store_dwordx4 v[8:9], v[2:5], off
	ds_read_b32 v2, v73 offset:64
	ds_read_b32 v3, v73 offset:196
	ds_read_b32 v4, v73 offset:328
	ds_read_b32 v5, v73 offset:460
	ds_read_b32 v8, v73 offset:592
	ds_read_b32 v9, v73 offset:724
	ds_read_b32 v10, v73 offset:856
	ds_read_b32 v11, v73 offset:988
	s_waitcnt lgkmcnt(0)
	v_bfe_u32 v12, v2, 16, 1
	v_add3_u32 v2, v2, v12, s35
	v_bfe_u32 v12, v3, 16, 1
	v_lshrrev_b32_e32 v2, 16, v2
	v_add3_u32 v3, v3, v12, s35
	v_and_or_b32 v2, v3, s36, v2
	v_bfe_u32 v3, v4, 16, 1
	v_add3_u32 v3, v4, v3, s35
	v_bfe_u32 v4, v5, 16, 1
	v_lshrrev_b32_e32 v3, 16, v3
	v_add3_u32 v4, v5, v4, s35
	v_and_or_b32 v3, v4, s36, v3
	v_bfe_u32 v4, v8, 16, 1
	v_add3_u32 v4, v8, v4, s35
	v_bfe_u32 v5, v9, 16, 1
	v_lshrrev_b32_e32 v4, 16, v4
	v_add3_u32 v5, v9, v5, s35
	v_and_or_b32 v4, v5, s36, v4
	v_bfe_u32 v5, v10, 16, 1
	v_add3_u32 v5, v10, v5, s35
	v_bfe_u32 v8, v11, 16, 1
	v_lshrrev_b32_e32 v5, 16, v5
	v_add3_u32 v8, v11, v8, s35
	v_and_or_b32 v5, v8, s36, v5
	v_or_b32_e32 v8, s0, v71
	v_lshlrev_b32_e32 v36, 10, v8
	v_lshl_add_u64 v[8:9], v[6:7], 0, v[36:37]
	global_store_dwordx4 v[8:9], v[2:5], off
	ds_read_b32 v2, v73 offset:96
	ds_read_b32 v3, v73 offset:228
	ds_read_b32 v4, v73 offset:360
	ds_read_b32 v5, v73 offset:492
	ds_read_b32 v8, v73 offset:624
	ds_read_b32 v9, v73 offset:756
	ds_read_b32 v10, v73 offset:888
	ds_read_b32 v11, v73 offset:1020
	s_waitcnt lgkmcnt(0)
	v_bfe_u32 v12, v2, 16, 1
	v_add3_u32 v2, v2, v12, s35
	v_bfe_u32 v12, v3, 16, 1
	v_lshrrev_b32_e32 v2, 16, v2
	v_add3_u32 v3, v3, v12, s35
	v_and_or_b32 v2, v3, s36, v2
	v_bfe_u32 v3, v4, 16, 1
	v_add3_u32 v3, v4, v3, s35
	v_bfe_u32 v4, v5, 16, 1
	v_lshrrev_b32_e32 v3, 16, v3
	v_add3_u32 v4, v5, v4, s35
	v_and_or_b32 v3, v4, s36, v3
	v_bfe_u32 v4, v8, 16, 1
	v_add3_u32 v4, v8, v4, s35
	v_bfe_u32 v5, v9, 16, 1
	v_lshrrev_b32_e32 v4, 16, v4
	v_add3_u32 v5, v9, v5, s35
	v_and_or_b32 v4, v5, s36, v4
	v_bfe_u32 v5, v10, 16, 1
	v_add3_u32 v5, v10, v5, s35
	v_bfe_u32 v8, v11, 16, 1
	v_lshrrev_b32_e32 v5, 16, v5
	v_add3_u32 v8, v11, v8, s35
	v_and_or_b32 v5, v8, s36, v5
	v_or_b32_e32 v8, s0, v72
	v_lshlrev_b32_e32 v36, 10, v8
	v_lshl_add_u64 v[6:7], v[6:7], 0, v[36:37]
	global_store_dwordx4 v[6:7], v[2:5], off
	s_waitcnt lgkmcnt(0)

.LBB0_47:
	s_andn2_b64 vcc, exec, s[6:7]
	s_cbranch_vccnz .LBB0_49
	s_and_b32 s6, s22, 0x3e0
	s_and_b32 s0, s27, 0x3fc0
	s_addk_i32 s0, 0xde00
	s_lshl_b32 s7, s6, 2
	s_add_u32 s18, s60, s7
	s_addc_u32 s19, s61, 0
	v_lshlrev_b32_e32 v36, 2, v34
	v_or_b32_e32 v32, s0, v35
	v_lshl_add_u64 v[2:3], s[18:19], 0, v[36:37]
	v_lshl_add_u64 v[30:31], v[2:3], 0, s[16:17]
	v_or_b32_e32 v4, 8, v32
	v_or_b32_e32 v10, 16, v32
	v_or_b32_e32 v12, 24, v32
	v_or_b32_e32 v18, 32, v32
	v_or_b32_e32 v20, 40, v32
	v_mad_u64_u32 v[2:3], s[18:19], v32, s42, v[30:31]
	v_mad_u64_u32 v[6:7], s[18:19], v4, s42, v[30:31]
	v_mad_u64_u32 v[10:11], s[18:19], v10, s42, v[30:31]
	v_mad_u64_u32 v[14:15], s[18:19], v12, s42, v[30:31]
	v_mad_u64_u32 v[18:19], s[18:19], v18, s42, v[30:31]
	v_mad_u64_u32 v[22:23], s[18:19], v20, s42, v[30:31]
	global_load_dwordx4 v[2:5], v[2:3], off
	s_nop 0
	global_load_dwordx4 v[6:9], v[6:7], off
	s_nop 0
	global_load_dwordx4 v[10:13], v[10:11], off
	s_nop 0
	global_load_dwordx4 v[14:17], v[14:15], off
	s_nop 0
	global_load_dwordx4 v[18:21], v[18:19], off
	s_nop 0
	global_load_dwordx4 v[22:25], v[22:23], off
	v_or_b32_e32 v26, 48, v32
	v_mad_u64_u32 v[26:27], s[18:19], v26, s42, v[30:31]
	global_load_dwordx4 v[26:29], v[26:27], off
	v_or_b32_e32 v32, 56, v32
	v_mad_u64_u32 v[30:31], s[18:19], v32, s42, v[30:31]
	global_load_dwordx4 v[30:33], v[30:31], off
	v_or_b32_e32 v36, s6, v35
	v_lshl_add_u64 v[68:69], s[0:1], 1, v[62:63]
	v_lshlrev_b32_e32 v36, 12, v36
	v_lshl_add_u64 v[90:91], v[68:69], 0, v[36:37]
	s_waitcnt vmcnt(0)
	ds_write2_b32 v74, v2, v3 offset1:1
	ds_write2_b32 v74, v4, v5 offset0:2 offset1:3
	ds_write2_b32 v75, v6, v7 offset1:1
	ds_write2_b32 v76, v8, v9 offset1:1
	ds_write2_b32 v77, v10, v11 offset1:1
	ds_write2_b32 v78, v12, v13 offset1:1
	ds_write2_b32 v79, v14, v15 offset1:1
	ds_write2_b32 v80, v16, v17 offset1:1
	ds_write2_b32 v81, v18, v19 offset1:1
	ds_write2_b32 v82, v20, v21 offset1:1
	ds_write2_b32 v83, v22, v23 offset1:1
	ds_write2_b32 v84, v24, v25 offset1:1
	ds_write2_b32 v85, v26, v27 offset1:1
	ds_write2_b32 v86, v28, v29 offset1:1
	ds_write2_b32 v87, v30, v31 offset1:1
	ds_write2_b32 v88, v32, v33 offset1:1
	s_waitcnt lgkmcnt(0)
	ds_read_b32 v2, v73
	ds_read_b32 v3, v73 offset:132
	ds_read_b32 v4, v73 offset:264
	ds_read_b32 v5, v73 offset:396
	ds_read_b32 v6, v73 offset:528
	ds_read_b32 v7, v73 offset:660
	ds_read_b32 v8, v73 offset:792
	ds_read_b32 v9, v73 offset:924
	s_waitcnt lgkmcnt(0)
	v_bfe_u32 v10, v2, 16, 1
	v_bfe_u32 v12, v4, 16, 1
	v_bfe_u32 v14, v6, 16, 1
	v_bfe_u32 v16, v8, 16, 1
	v_bfe_u32 v11, v3, 16, 1
	v_bfe_u32 v13, v5, 16, 1
	v_bfe_u32 v15, v7, 16, 1
	v_bfe_u32 v17, v9, 16, 1
	v_add3_u32 v2, v2, v10, s35
	v_add3_u32 v4, v4, v12, s35
	v_add3_u32 v6, v6, v14, s35
	v_add3_u32 v8, v8, v16, s35
	v_add3_u32 v3, v3, v11, s35
	v_add3_u32 v5, v5, v13, s35
	v_add3_u32 v7, v7, v15, s35
	v_add3_u32 v9, v9, v17, s35
	v_lshrrev_b32_e32 v2, 16, v2
	v_lshrrev_b32_e32 v4, 16, v4
	v_lshrrev_b32_e32 v6, 16, v6
	v_lshrrev_b32_e32 v8, 16, v8
	v_and_or_b32 v2, v3, s36, v2
	v_and_or_b32 v3, v5, s36, v4
	v_and_or_b32 v4, v7, s36, v6
	v_and_or_b32 v5, v9, s36, v8
	global_store_dwordx4 v[90:91], v[2:5], off
	ds_read_b32 v2, v73 offset:32
	ds_read_b32 v3, v73 offset:164
	ds_read_b32 v4, v73 offset:296
	ds_read_b32 v5, v73 offset:428
	ds_read_b32 v6, v73 offset:560
	ds_read_b32 v7, v73 offset:692
	ds_read_b32 v8, v73 offset:824
	ds_read_b32 v9, v73 offset:956
	s_waitcnt lgkmcnt(0)
	v_bfe_u32 v10, v2, 16, 1
	v_bfe_u32 v11, v3, 16, 1
	v_add3_u32 v2, v2, v10, s35
	v_lshrrev_b32_e32 v2, 16, v2
	v_add3_u32 v3, v3, v11, s35
	v_and_or_b32 v2, v3, s36, v2
	v_bfe_u32 v3, v4, 16, 1
	v_add3_u32 v3, v4, v3, s35
	v_bfe_u32 v4, v5, 16, 1
	v_lshrrev_b32_e32 v3, 16, v3
	v_add3_u32 v4, v5, v4, s35
	v_and_or_b32 v3, v4, s36, v3
	v_bfe_u32 v4, v6, 16, 1
	v_add3_u32 v4, v6, v4, s35
	v_bfe_u32 v5, v7, 16, 1
	v_lshrrev_b32_e32 v4, 16, v4
	v_add3_u32 v5, v7, v5, s35
	v_and_or_b32 v4, v5, s36, v4
	v_bfe_u32 v5, v8, 16, 1
	v_add3_u32 v5, v8, v5, s35
	v_bfe_u32 v6, v9, 16, 1
	v_lshrrev_b32_e32 v5, 16, v5
	v_add3_u32 v6, v9, v6, s35
	v_and_or_b32 v5, v6, s36, v5
	v_or_b32_e32 v6, s6, v70
	v_lshlrev_b32_e32 v36, 12, v6
	v_lshl_add_u64 v[6:7], v[68:69], 0, v[36:37]
	global_store_dwordx4 v[6:7], v[2:5], off
	ds_read_b32 v2, v73 offset:64
	ds_read_b32 v3, v73 offset:196
	ds_read_b32 v4, v73 offset:328
	ds_read_b32 v5, v73 offset:460
	ds_read_b32 v6, v73 offset:592
	ds_read_b32 v7, v73 offset:724
	ds_read_b32 v8, v73 offset:856
	ds_read_b32 v9, v73 offset:988
	s_waitcnt lgkmcnt(0)
	v_bfe_u32 v10, v2, 16, 1
	v_add3_u32 v2, v2, v10, s35
	v_bfe_u32 v10, v3, 16, 1
	v_lshrrev_b32_e32 v2, 16, v2
	v_add3_u32 v3, v3, v10, s35
	v_and_or_b32 v2, v3, s36, v2
	v_bfe_u32 v3, v4, 16, 1
	v_add3_u32 v3, v4, v3, s35
	v_bfe_u32 v4, v5, 16, 1
	v_lshrrev_b32_e32 v3, 16, v3
	v_add3_u32 v4, v5, v4, s35
	v_and_or_b32 v3, v4, s36, v3
	v_bfe_u32 v4, v6, 16, 1
	v_add3_u32 v4, v6, v4, s35
	v_bfe_u32 v5, v7, 16, 1
	v_lshrrev_b32_e32 v4, 16, v4
	v_add3_u32 v5, v7, v5, s35
	v_and_or_b32 v4, v5, s36, v4
	v_bfe_u32 v5, v8, 16, 1
	v_add3_u32 v5, v8, v5, s35
	v_bfe_u32 v6, v9, 16, 1
	v_lshrrev_b32_e32 v5, 16, v5
	v_add3_u32 v6, v9, v6, s35
	v_and_or_b32 v5, v6, s36, v5
	v_or_b32_e32 v6, s6, v71
	v_lshlrev_b32_e32 v36, 12, v6
	v_lshl_add_u64 v[6:7], v[68:69], 0, v[36:37]
	global_store_dwordx4 v[6:7], v[2:5], off
	ds_read_b32 v2, v73 offset:96
	ds_read_b32 v3, v73 offset:228
	ds_read_b32 v4, v73 offset:360
	ds_read_b32 v5, v73 offset:492
	ds_read_b32 v6, v73 offset:624
	ds_read_b32 v7, v73 offset:756
	ds_read_b32 v8, v73 offset:888
	ds_read_b32 v9, v73 offset:1020
	s_waitcnt lgkmcnt(0)
	v_bfe_u32 v10, v2, 16, 1
	v_add3_u32 v2, v2, v10, s35
	v_bfe_u32 v10, v3, 16, 1
	v_lshrrev_b32_e32 v2, 16, v2
	v_add3_u32 v3, v3, v10, s35
	v_and_or_b32 v2, v3, s36, v2
	v_bfe_u32 v3, v4, 16, 1
	v_add3_u32 v3, v4, v3, s35
	v_bfe_u32 v4, v5, 16, 1
	v_lshrrev_b32_e32 v3, 16, v3
	v_add3_u32 v4, v5, v4, s35
	v_and_or_b32 v3, v4, s36, v3
	v_bfe_u32 v4, v6, 16, 1
	v_add3_u32 v4, v6, v4, s35
	v_bfe_u32 v5, v7, 16, 1
	v_lshrrev_b32_e32 v4, 16, v4
	v_add3_u32 v5, v7, v5, s35
	v_and_or_b32 v4, v5, s36, v4
	v_bfe_u32 v5, v8, 16, 1
	v_add3_u32 v5, v8, v5, s35
	v_bfe_u32 v6, v9, 16, 1
	v_lshrrev_b32_e32 v5, 16, v5
	v_add3_u32 v6, v9, v6, s35
	v_and_or_b32 v5, v6, s36, v5
	v_or_b32_e32 v6, s6, v72
	v_lshlrev_b32_e32 v36, 12, v6
	v_lshl_add_u64 v[6:7], v[68:69], 0, v[36:37]
	global_store_dwordx4 v[6:7], v[2:5], off
	s_waitcnt lgkmcnt(0)

.Lmy_rms_nopf:
	v_mul_f32_e32 v84, v14, v14
	v_pk_mul_f32 v[62:63], v[12:13], v[12:13]
	v_pk_mul_f32 v[64:65], v[10:11], v[10:11]
	v_mul_f32_e32 v32, v7, v7
	v_mul_f32_e32 v66, v9, v9
	v_mul_f32_e32 v83, v4, v4
	v_mul_f32_e32 v90, v5, v5
	v_mov_b32_e32 v68, v42
	v_mov_b32_e32 v69, v44
	v_mov_b32_e32 v44, v43
	v_pk_mov_b32 v[42:43], v[64:65], v[62:63] op_sel:[1,0]
	v_mov_b32_e32 v65, v63
	v_pk_fma_f32 v[62:63], v[6:7], v[6:7], v[32:33] op_sel_hi:[1,1,0]
	v_pk_fma_f32 v[66:67], v[8:9], v[8:9], v[66:67] op_sel_hi:[1,1,0]
	v_mov_b32_e32 v72, v47
	v_mov_b32_e32 v73, v51
	v_mov_b32_e32 v76, v49
	v_mov_b32_e32 v77, v53
	v_mov_b32_e32 v70, v46
	v_mov_b32_e32 v71, v50
	v_mov_b32_e32 v74, v48
	v_mov_b32_e32 v75, v52
	v_pk_mul_f32 v[78:79], v[56:57], v[56:57]
	v_pk_mul_f32 v[80:81], v[54:55], v[54:55]
	v_pk_add_f32 v[42:43], v[42:43], v[64:65]
	v_mov_b32_e32 v63, v83
	v_mov_b32_e32 v67, v90
	v_mov_b32_e32 v64, v46
	v_mov_b32_e32 v65, v48
	v_mov_b32_e32 v48, v47
	v_mov_b32_e32 v46, v50
	v_mov_b32_e32 v47, v52
	v_mov_b32_e32 v52, v51
	v_pk_mul_f32 v[50:51], v[72:73], v[72:73]
	v_pk_mul_f32 v[72:73], v[76:77], v[76:77]
	v_pk_mov_b32 v[76:77], v[80:81], v[78:79] op_sel:[1,0]
	v_mov_b32_e32 v81, v79
	v_pk_add_f32 v[62:63], v[62:63], v[66:67]
	v_pk_fma_f32 v[50:51], v[70:71], v[70:71], v[50:51]
	v_pk_fma_f32 v[66:67], v[74:75], v[74:75], v[72:73]
	v_mul_f32_e32 v32, v59, v59
	v_mul_f32_e32 v82, v61, v61
	v_pk_add_f32 v[70:71], v[76:77], v[80:81]
	v_pk_add_f32 v[50:51], v[50:51], v[66:67]
	v_mul_f32_e32 v85, v15, v15
	v_mul_f32_e32 v86, v16, v16
	v_mul_f32_e32 v87, v17, v17
	v_pk_fma_f32 v[78:79], v[58:59], v[58:59], v[32:33] op_sel_hi:[1,1,0]
	v_pk_fma_f32 v[82:83], v[60:61], v[60:61], v[82:83] op_sel_hi:[1,1,0]
	v_pk_add_f32 v[66:67], v[70:71], v[70:71] op_sel:[0,1] op_sel_hi:[1,0]
	v_pk_add_f32 v[50:51], v[50:51], v[50:51] op_sel:[0,1] op_sel_hi:[1,0]
	v_mov_b32_e32 v79, v86
	v_mov_b32_e32 v83, v87
	v_mov_b32_e32 v67, v85
	v_mov_b32_e32 v51, v84
	v_pk_add_f32 v[70:71], v[78:79], v[82:83]
	v_pk_add_f32 v[50:51], v[50:51], v[66:67]
	v_mul_f32_e32 v88, v2, v2
	v_pk_add_f32 v[50:51], v[50:51], v[70:71]
	v_mul_f32_e32 v89, v3, v3
	v_pk_add_f32 v[42:43], v[42:43], v[42:43] op_sel:[0,1] op_sel_hi:[1,0]
	v_pk_add_f32 v[50:51], v[50:51], v[50:51] op_sel:[0,1] op_sel_hi:[1,0]
	v_mov_b32_e32 v43, v89
	v_mov_b32_e32 v51, v88
	v_pk_add_f32 v[42:43], v[50:51], v[42:43]
	s_nop 0
	v_pk_add_f32 v[42:43], v[42:43], v[62:63]
	s_nop 0
	v_add_f32_e32 v32, v42, v43
	ds_bpermute_b32 v42, v33, v32
	s_waitcnt lgkmcnt(0)
	v_add_f32_e32 v32, v32, v42
	ds_bpermute_b32 v42, v34, v32
	s_waitcnt lgkmcnt(0)
	v_add_f32_e32 v32, v32, v42
	ds_bpermute_b32 v42, v35, v32
	s_waitcnt lgkmcnt(0)
	v_add_f32_e32 v32, v32, v42
	ds_bpermute_b32 v42, v36, v32
	s_waitcnt lgkmcnt(0)
	v_add_f32_e32 v32, v32, v42
	ds_bpermute_b32 v42, v37, v32
	s_waitcnt lgkmcnt(0)
	v_add_f32_e32 v32, v32, v42
	ds_bpermute_b32 v42, v38, v32
	s_waitcnt lgkmcnt(0)
	v_add_f32_e32 v32, v32, v42
	v_fmamk_f32 v32, v32, 0x3a000000, v39
	v_mul_f32_e32 v42, 0x4f800000, v32
	v_cmp_gt_f32_e32 vcc, s12, v32
	s_nop 1
	v_cndmask_b32_e32 v32, v32, v42, vcc
	v_sqrt_f32_e32 v42, v32
	s_nop 0
	v_add_u32_e32 v43, -1, v42
	v_add_u32_e32 v50, 1, v42
	v_fma_f32 v51, -v43, v42, v32
	v_fma_f32 v62, -v50, v42, v32
	v_cmp_ge_f32_e64 s[0:1], 0, v51
	s_nop 1
	v_cndmask_b32_e64 v42, v42, v43, s[0:1]
	v_cmp_lt_f32_e64 s[0:1], 0, v62
	s_nop 1
	v_cndmask_b32_e64 v42, v42, v50, s[0:1]
	v_mul_f32_e32 v43, 0x37800000, v42
	v_cndmask_b32_e32 v42, v42, v43, vcc
	v_cmp_class_f32_e32 vcc, v32, v40
	s_nop 1
	v_cndmask_b32_e32 v32, v42, v32, vcc
	v_div_scale_f32 v42, s[0:1], v32, v32, 1.0
	v_rcp_f32_e32 v50, v42
	v_div_scale_f32 v43, vcc, 1.0, v32, 1.0
	v_fma_f32 v51, -v42, v50, 1.0
	v_fmac_f32_e32 v50, v51, v50
	v_mul_f32_e32 v51, v43, v50
	v_fma_f32 v62, -v42, v51, v43
	v_fmac_f32_e32 v51, v62, v50
	v_fma_f32 v42, -v42, v51, v43
	v_div_fmas_f32 v42, v42, v50, v51
	v_div_fixup_f32 v32, v42, v32, 1.0
	v_pk_mul_f32 v[48:49], v[32:33], v[48:49] op_sel_hi:[0,1]
	v_pk_mul_f32 v[42:43], v[32:33], v[64:65] op_sel_hi:[0,1]
	v_pk_mul_f32 v[44:45], v[48:49], v[44:45]
	v_pk_mul_f32 v[42:43], v[42:43], v[68:69]
	v_and_b32_sdwa v50, v45, v41 dst_sel:DWORD dst_unused:UNUSED_PAD src0_sel:WORD_1 src1_sel:DWORD
	v_and_b32_sdwa v51, v44, v41 dst_sel:DWORD dst_unused:UNUSED_PAD src0_sel:WORD_1 src1_sel:DWORD
	v_and_b32_sdwa v48, v43, v41 dst_sel:DWORD dst_unused:UNUSED_PAD src0_sel:WORD_1 src1_sel:DWORD
	v_and_b32_sdwa v49, v42, v41 dst_sel:DWORD dst_unused:UNUSED_PAD src0_sel:WORD_1 src1_sel:DWORD
	v_add3_u32 v45, v45, v50, s13
	v_add3_u32 v44, v44, v51, s13
	v_add3_u32 v42, v42, v49, s13
	v_add3_u32 v43, v43, v48, s13
	v_and_b32_e32 v45, 0xffff0000, v45
	v_and_b32_e32 v44, 0xffff0000, v44
	v_or_b32_sdwa v43, v45, v43 dst_sel:DWORD dst_unused:UNUSED_PAD src0_sel:DWORD src1_sel:WORD_1
	v_or_b32_sdwa v42, v44, v42 dst_sel:DWORD dst_unused:UNUSED_PAD src0_sel:DWORD src1_sel:WORD_1
	global_store_dwordx2 v[28:29], v[42:43], off
	v_pk_mul_f32 v[48:49], v[32:33], v[52:53] op_sel_hi:[0,1]
	v_pk_mul_f32 v[46:47], v[32:33], v[46:47] op_sel_hi:[0,1]
	v_mov_b64_e32 v[42:43], v[144:145]
	v_mov_b64_e32 v[44:45], v[146:147]
	v_mov_b32_e32 v51, v44
	v_mov_b32_e32 v44, v43
	v_mov_b32_e32 v50, v42
	v_pk_mul_f32 v[44:45], v[48:49], v[44:45]
	v_pk_mul_f32 v[42:43], v[46:47], v[50:51]
	v_and_b32_sdwa v48, v45, v41 dst_sel:DWORD dst_unused:UNUSED_PAD src0_sel:WORD_1 src1_sel:DWORD
	v_and_b32_sdwa v49, v44, v41 dst_sel:DWORD dst_unused:UNUSED_PAD src0_sel:WORD_1 src1_sel:DWORD
	v_and_b32_sdwa v46, v43, v41 dst_sel:DWORD dst_unused:UNUSED_PAD src0_sel:WORD_1 src1_sel:DWORD
	v_and_b32_sdwa v47, v42, v41 dst_sel:DWORD dst_unused:UNUSED_PAD src0_sel:WORD_1 src1_sel:DWORD
	v_add3_u32 v45, v45, v48, s13
	v_add3_u32 v44, v44, v49, s13
	v_add3_u32 v42, v42, v47, s13
	v_add3_u32 v43, v43, v46, s13
	v_and_b32_e32 v45, 0xffff0000, v45
	v_and_b32_e32 v44, 0xffff0000, v44
	v_or_b32_sdwa v43, v45, v43 dst_sel:DWORD dst_unused:UNUSED_PAD src0_sel:DWORD src1_sel:WORD_1
	v_or_b32_sdwa v42, v44, v42 dst_sel:DWORD dst_unused:UNUSED_PAD src0_sel:DWORD src1_sel:WORD_1
	global_store_dwordx2 v[28:29], v[42:43], off offset:512
	v_mov_b32_e32 v47, v56
	v_mov_b32_e32 v56, v55
	v_mov_b32_e32 v46, v54
	v_pk_mul_f32 v[48:49], v[32:33], v[56:57] op_sel_hi:[0,1]
	v_pk_mul_f32 v[46:47], v[32:33], v[46:47] op_sel_hi:[0,1]
	v_mov_b64_e32 v[42:43], v[148:149]
	v_mov_b64_e32 v[44:45], v[150:151]
	v_mov_b32_e32 v51, v44
	v_mov_b32_e32 v44, v43
	v_mov_b32_e32 v50, v42
	v_pk_mul_f32 v[44:45], v[48:49], v[44:45]
	v_pk_mul_f32 v[42:43], v[46:47], v[50:51]
	v_and_b32_sdwa v48, v45, v41 dst_sel:DWORD dst_unused:UNUSED_PAD src0_sel:WORD_1 src1_sel:DWORD
	v_and_b32_sdwa v49, v44, v41 dst_sel:DWORD dst_unused:UNUSED_PAD src0_sel:WORD_1 src1_sel:DWORD
	v_and_b32_sdwa v46, v43, v41 dst_sel:DWORD dst_unused:UNUSED_PAD src0_sel:WORD_1 src1_sel:DWORD
	v_and_b32_sdwa v47, v42, v41 dst_sel:DWORD dst_unused:UNUSED_PAD src0_sel:WORD_1 src1_sel:DWORD
	v_add3_u32 v45, v45, v48, s13
	v_add3_u32 v44, v44, v49, s13
	v_add3_u32 v42, v42, v47, s13
	v_add3_u32 v43, v43, v46, s13
	v_and_b32_e32 v45, 0xffff0000, v45
	v_and_b32_e32 v44, 0xffff0000, v44
	v_or_b32_sdwa v43, v45, v43 dst_sel:DWORD dst_unused:UNUSED_PAD src0_sel:DWORD src1_sel:WORD_1
	v_or_b32_sdwa v42, v44, v42 dst_sel:DWORD dst_unused:UNUSED_PAD src0_sel:DWORD src1_sel:WORD_1
	global_store_dwordx2 v[28:29], v[42:43], off offset:1024
	v_mov_b32_e32 v47, v60
	v_mov_b32_e32 v60, v59
	v_mov_b32_e32 v46, v58
	v_pk_mul_f32 v[48:49], v[32:33], v[60:61] op_sel_hi:[0,1]
	v_pk_mul_f32 v[46:47], v[32:33], v[46:47] op_sel_hi:[0,1]
	v_mov_b64_e32 v[42:43], v[152:153]
	v_mov_b64_e32 v[44:45], v[154:155]
	v_mov_b32_e32 v51, v44
	v_mov_b32_e32 v44, v43
	v_mov_b32_e32 v50, v42
	v_pk_mul_f32 v[44:45], v[48:49], v[44:45]
	v_pk_mul_f32 v[42:43], v[46:47], v[50:51]
	v_and_b32_sdwa v48, v45, v41 dst_sel:DWORD dst_unused:UNUSED_PAD src0_sel:WORD_1 src1_sel:DWORD
	v_and_b32_sdwa v49, v44, v41 dst_sel:DWORD dst_unused:UNUSED_PAD src0_sel:WORD_1 src1_sel:DWORD
	v_and_b32_sdwa v46, v43, v41 dst_sel:DWORD dst_unused:UNUSED_PAD src0_sel:WORD_1 src1_sel:DWORD
	v_and_b32_sdwa v47, v42, v41 dst_sel:DWORD dst_unused:UNUSED_PAD src0_sel:WORD_1 src1_sel:DWORD
	v_add3_u32 v45, v45, v48, s13
	v_add3_u32 v44, v44, v49, s13
	v_add3_u32 v42, v42, v47, s13
	v_add3_u32 v43, v43, v46, s13
	v_and_b32_e32 v45, 0xffff0000, v45
	v_and_b32_e32 v44, 0xffff0000, v44
	v_or_b32_sdwa v43, v45, v43 dst_sel:DWORD dst_unused:UNUSED_PAD src0_sel:DWORD src1_sel:WORD_1
	v_or_b32_sdwa v42, v44, v42 dst_sel:DWORD dst_unused:UNUSED_PAD src0_sel:DWORD src1_sel:WORD_1
	global_store_dwordx2 v[28:29], v[42:43], off offset:1536
	v_mov_b32_e32 v46, v14
	v_mov_b32_e32 v47, v16
	v_mov_b32_e32 v16, v15
	v_pk_mul_f32 v[14:15], v[32:33], v[46:47] op_sel_hi:[0,1]
	v_pk_mul_f32 v[16:17], v[32:33], v[16:17] op_sel_hi:[0,1]
	v_mov_b64_e32 v[42:43], v[156:157]
	v_mov_b64_e32 v[44:45], v[158:159]
	v_mov_b32_e32 v47, v44
	v_mov_b32_e32 v44, v43
	v_mov_b32_e32 v46, v42
	v_pk_mul_f32 v[16:17], v[16:17], v[44:45]
	v_pk_mul_f32 v[14:15], v[14:15], v[46:47]
	v_and_b32_sdwa v44, v17, v41 dst_sel:DWORD dst_unused:UNUSED_PAD src0_sel:WORD_1 src1_sel:DWORD
	v_and_b32_sdwa v45, v16, v41 dst_sel:DWORD dst_unused:UNUSED_PAD src0_sel:WORD_1 src1_sel:DWORD
	v_and_b32_sdwa v42, v15, v41 dst_sel:DWORD dst_unused:UNUSED_PAD src0_sel:WORD_1 src1_sel:DWORD
	v_and_b32_sdwa v43, v14, v41 dst_sel:DWORD dst_unused:UNUSED_PAD src0_sel:WORD_1 src1_sel:DWORD
	v_add3_u32 v17, v17, v44, s13
	v_add3_u32 v16, v16, v45, s13
	v_add3_u32 v14, v14, v43, s13
	v_add3_u32 v15, v15, v42, s13
	v_and_b32_e32 v17, 0xffff0000, v17
	v_and_b32_e32 v16, 0xffff0000, v16
	v_or_b32_sdwa v15, v17, v15 dst_sel:DWORD dst_unused:UNUSED_PAD src0_sel:DWORD src1_sel:WORD_1
	v_or_b32_sdwa v14, v16, v14 dst_sel:DWORD dst_unused:UNUSED_PAD src0_sel:DWORD src1_sel:WORD_1
	global_store_dwordx2 v[28:29], v[14:15], off offset:2048
	v_mov_b32_e32 v42, v10
	v_mov_b32_e32 v43, v12
	v_mov_b32_e32 v12, v11
	v_pk_mul_f32 v[10:11], v[32:33], v[42:43] op_sel_hi:[0,1]
	v_pk_mul_f32 v[12:13], v[32:33], v[12:13] op_sel_hi:[0,1]
	v_mov_b64_e32 v[14:15], v[160:161]
	v_mov_b64_e32 v[16:17], v[162:163]
	v_mov_b32_e32 v43, v16
	v_mov_b32_e32 v16, v15
	v_mov_b32_e32 v42, v14
	v_pk_mul_f32 v[12:13], v[12:13], v[16:17]
	v_pk_mul_f32 v[10:11], v[10:11], v[42:43]
	v_and_b32_sdwa v16, v13, v41 dst_sel:DWORD dst_unused:UNUSED_PAD src0_sel:WORD_1 src1_sel:DWORD
	v_and_b32_sdwa v17, v12, v41 dst_sel:DWORD dst_unused:UNUSED_PAD src0_sel:WORD_1 src1_sel:DWORD
	v_and_b32_sdwa v14, v11, v41 dst_sel:DWORD dst_unused:UNUSED_PAD src0_sel:WORD_1 src1_sel:DWORD
	v_and_b32_sdwa v15, v10, v41 dst_sel:DWORD dst_unused:UNUSED_PAD src0_sel:WORD_1 src1_sel:DWORD
	v_add3_u32 v13, v13, v16, s13
	v_add3_u32 v12, v12, v17, s13
	v_add3_u32 v10, v10, v15, s13
	v_add3_u32 v11, v11, v14, s13
	v_and_b32_e32 v13, 0xffff0000, v13
	v_and_b32_e32 v12, 0xffff0000, v12
	v_or_b32_sdwa v11, v13, v11 dst_sel:DWORD dst_unused:UNUSED_PAD src0_sel:DWORD src1_sel:WORD_1
	v_or_b32_sdwa v10, v12, v10 dst_sel:DWORD dst_unused:UNUSED_PAD src0_sel:DWORD src1_sel:WORD_1
	global_store_dwordx2 v[28:29], v[10:11], off offset:2560
	v_mov_b32_e32 v14, v6
	v_mov_b32_e32 v15, v8
	v_mov_b32_e32 v8, v7
	v_pk_mul_f32 v[6:7], v[32:33], v[14:15] op_sel_hi:[0,1]
	v_pk_mul_f32 v[8:9], v[32:33], v[8:9] op_sel_hi:[0,1]
	v_mov_b64_e32 v[10:11], v[164:165]
	v_mov_b64_e32 v[12:13], v[166:167]
	v_mov_b32_e32 v15, v12
	v_mov_b32_e32 v12, v11
	v_mov_b32_e32 v14, v10
	v_pk_mul_f32 v[8:9], v[8:9], v[12:13]
	v_pk_mul_f32 v[6:7], v[6:7], v[14:15]
	v_and_b32_sdwa v12, v9, v41 dst_sel:DWORD dst_unused:UNUSED_PAD src0_sel:WORD_1 src1_sel:DWORD
	v_and_b32_sdwa v13, v8, v41 dst_sel:DWORD dst_unused:UNUSED_PAD src0_sel:WORD_1 src1_sel:DWORD
	v_and_b32_sdwa v10, v7, v41 dst_sel:DWORD dst_unused:UNUSED_PAD src0_sel:WORD_1 src1_sel:DWORD
	v_and_b32_sdwa v11, v6, v41 dst_sel:DWORD dst_unused:UNUSED_PAD src0_sel:WORD_1 src1_sel:DWORD
	v_add3_u32 v9, v9, v12, s13
	v_add3_u32 v8, v8, v13, s13
	v_add3_u32 v6, v6, v11, s13
	v_add3_u32 v7, v7, v10, s13
	v_and_b32_e32 v9, 0xffff0000, v9
	v_and_b32_e32 v8, 0xffff0000, v8
	v_or_b32_sdwa v7, v9, v7 dst_sel:DWORD dst_unused:UNUSED_PAD src0_sel:DWORD src1_sel:WORD_1
	v_or_b32_sdwa v6, v8, v6 dst_sel:DWORD dst_unused:UNUSED_PAD src0_sel:DWORD src1_sel:WORD_1
	global_store_dwordx2 v[28:29], v[6:7], off offset:3072
	v_mov_b32_e32 v10, v2
	v_mov_b32_e32 v11, v4
	v_mov_b32_e32 v4, v3
	v_pk_mul_f32 v[2:3], v[32:33], v[10:11] op_sel_hi:[0,1]
	v_pk_mul_f32 v[4:5], v[32:33], v[4:5] op_sel_hi:[0,1]
	v_mov_b64_e32 v[6:7], v[168:169]
	v_mov_b64_e32 v[8:9], v[170:171]
	v_mov_b32_e32 v11, v8
	v_mov_b32_e32 v8, v7
	v_mov_b32_e32 v10, v6
	v_pk_mul_f32 v[4:5], v[4:5], v[8:9]
	v_pk_mul_f32 v[2:3], v[2:3], v[10:11]
	v_and_b32_sdwa v8, v5, v41 dst_sel:DWORD dst_unused:UNUSED_PAD src0_sel:WORD_1 src1_sel:DWORD
	v_and_b32_sdwa v9, v4, v41 dst_sel:DWORD dst_unused:UNUSED_PAD src0_sel:WORD_1 src1_sel:DWORD
	v_and_b32_sdwa v6, v3, v41 dst_sel:DWORD dst_unused:UNUSED_PAD src0_sel:WORD_1 src1_sel:DWORD
	v_and_b32_sdwa v7, v2, v41 dst_sel:DWORD dst_unused:UNUSED_PAD src0_sel:WORD_1 src1_sel:DWORD
	v_add3_u32 v5, v5, v8, s13
	v_add3_u32 v4, v4, v9, s13
	v_add3_u32 v2, v2, v7, s13
	v_add3_u32 v3, v3, v6, s13
	v_and_b32_e32 v5, 0xffff0000, v5
	v_and_b32_e32 v4, 0xffff0000, v4
	v_or_b32_sdwa v3, v5, v3 dst_sel:DWORD dst_unused:UNUSED_PAD src0_sel:DWORD src1_sel:WORD_1
	v_or_b32_sdwa v2, v4, v2 dst_sel:DWORD dst_unused:UNUSED_PAD src0_sel:DWORD src1_sel:WORD_1
	global_store_dwordx2 v[28:29], v[2:3], off offset:3584
	v_lshl_add_u64 v[28:29], v[28:29], 0, s[6:7]
	s_cbranch_scc0 .LBB0_85

.LBB0_88:
	global_load_dwordx4 v[8:11], v[2:3], off
	v_add_u32_e32 v6, s74, v6
	v_cmp_lt_i32_e32 vcc, s16, v6
	v_lshl_add_u64 v[2:3], v[2:3], 0, s[6:7]
	s_or_b64 s[12:13], vcc, s[12:13]
	s_waitcnt vmcnt(0)
	v_bfe_u32 v7, v8, 16, 1
	v_bfe_u32 v12, v9, 16, 1
	v_bfe_u32 v13, v10, 16, 1
	v_bfe_u32 v14, v11, 16, 1
	v_add3_u32 v7, v8, v7, s14
	v_add3_u32 v8, v9, v12, s14
	v_add3_u32 v9, v10, v13, s14
	v_add3_u32 v10, v11, v14, s14
	v_lshrrev_b32_e32 v7, 16, v7
	v_lshrrev_b32_e32 v9, 16, v9
	v_and_or_b32 v8, v8, s15, v7
	v_and_or_b32 v9, v10, s15, v9
	global_store_dwordx2 v[4:5], v[8:9], off
	v_lshl_add_u64 v[4:5], v[4:5], 0, s[10:11]
	s_andn2_b64 exec, exec, s[12:13]
	s_cbranch_execnz .LBB0_88

.LBB0_91:
	s_or_b64 exec, exec, s[82:83]
	global_load_dword v2, v[12:13], off
	s_waitcnt vmcnt(1)
	v_cvt_f32_i32_e32 v5, v5
	v_lshl_add_u64 v[12:13], s[8:9], 0, v[14:15]
	v_lshlrev_b64 v[6:7], v10, v[6:7]
	v_lshl_add_u64 v[6:7], v[12:13], 0, v[6:7]
	v_lshl_add_u64 v[6:7], v[8:9], 3, v[6:7]
	s_mov_b32 s80, s78
	v_add_u32_e32 v4, s74, v4
	v_cmp_lt_i32_e32 vcc, s35, v4
	s_or_b64 s[6:7], vcc, s[6:7]
	s_waitcnt vmcnt(0)
	v_mul_f32_e32 v2, v2, v5
	v_cvt_f64_f32_e32 v[8:9], v2
	v_mul_f64 v[10:11], v[8:9], s[10:11]
	v_rndne_f64_e32 v[10:11], v[10:11]
	v_fma_f64 v[8:9], v[8:9], s[10:11], -v[10:11]
	v_mul_f64 v[8:9], v[8:9], s[12:13]
	v_mul_f64 v[10:11], v[8:9], v[8:9]
	v_fma_f64 v[12:13], v[10:11], s[14:15], 1.0
	v_fma_f64 v[14:15], v[10:11], s[16:17], 1.0
	v_mul_f64 v[12:13], v[10:11], v[12:13]
	v_mul_f64 v[14:15], v[10:11], v[14:15]
	v_fma_f64 v[12:13], v[12:13], s[18:19], 1.0
	v_fma_f64 v[14:15], v[14:15], s[20:21], 1.0
	v_mul_f64 v[12:13], v[10:11], v[12:13]
	v_mul_f64 v[14:15], v[10:11], v[14:15]
	v_fma_f64 v[12:13], v[12:13], s[22:23], 1.0
	v_fma_f64 v[14:15], v[14:15], s[24:25], 1.0
	v_mul_f64 v[12:13], v[10:11], v[12:13]
	v_mul_f64 v[14:15], v[10:11], v[14:15]
	v_fma_f64 v[12:13], v[12:13], s[36:37], 1.0
	v_fma_f64 v[14:15], v[14:15], s[38:39], 1.0
	v_mul_f64 v[12:13], v[10:11], v[12:13]
	v_mul_f64 v[14:15], v[10:11], v[14:15]
	v_fma_f64 v[12:13], v[12:13], s[40:41], 1.0
	v_fma_f64 v[14:15], v[14:15], s[42:43], 1.0
	v_mul_f64 v[12:13], v[10:11], v[12:13]
	v_mul_f64 v[14:15], v[10:11], v[14:15]
	v_fma_f64 v[12:13], v[12:13], s[44:45], 1.0
	v_fma_f64 v[14:15], v[14:15], s[46:47], 1.0
	v_mul_f64 v[12:13], v[10:11], v[12:13]
	v_mul_f64 v[14:15], v[10:11], v[14:15]
	v_fma_f64 v[12:13], v[12:13], s[50:51], 1.0
	v_fma_f64 v[14:15], v[14:15], s[54:55], 1.0
	v_mul_f64 v[12:13], v[10:11], v[12:13]
	v_mul_f64 v[14:15], v[10:11], v[14:15]
	v_fma_f64 v[12:13], v[12:13], s[58:59], 1.0
	v_fma_f64 v[14:15], v[14:15], s[60:61], 1.0
	v_mul_f64 v[12:13], v[10:11], v[12:13]
	v_mul_f64 v[14:15], v[10:11], v[14:15]
	v_fma_f64 v[12:13], v[12:13], s[62:63], 1.0
	v_fma_f64 v[14:15], v[14:15], s[64:65], 1.0
	v_mul_f64 v[12:13], v[10:11], v[12:13]
	v_mul_f64 v[14:15], v[10:11], v[14:15]
	v_fma_f64 v[12:13], v[12:13], s[66:67], 1.0
	v_fma_f64 v[14:15], v[14:15], s[70:71], 1.0
	v_mul_f64 v[12:13], v[10:11], v[12:13]
	v_mul_f64 v[14:15], v[10:11], v[14:15]
	v_fma_f64 v[12:13], v[12:13], s[72:73], 1.0
	v_fma_f64 v[14:15], v[14:15], s[48:49], 1.0
	v_mul_f64 v[12:13], v[10:11], v[12:13]
	v_mul_f64 v[14:15], v[10:11], v[14:15]
	v_fma_f64 v[12:13], v[12:13], s[76:77], 1.0
	v_fma_f64 v[14:15], v[14:15], s[78:79], 1.0
	v_mul_f64 v[12:13], v[10:11], v[12:13]
	v_mul_f64 v[10:11], v[10:11], v[14:15]
	v_fma_f64 v[12:13], v[12:13], s[80:81], 1.0
	v_fma_f64 v[10:11], v[10:11], -0.5, 1.0
	v_mul_f64 v[8:9], v[8:9], v[12:13]
	v_cvt_f32_f64_e32 v10, v[10:11]
	v_cvt_f32_f64_e32 v11, v[8:9]
	global_store_dwordx2 v[6:7], v[10:11], off
	s_andn2_b64 exec, exec, s[6:7]
	s_cbranch_execz .LBB0_96

.LBB0_99:
	v_add_u32_e32 v8, -2, v8
	v_ashrrev_i32_e32 v11, 31, v3
	v_mov_b32_e32 v10, v3
	v_ashrrev_i32_e32 v13, 31, v2
	v_mov_b32_e32 v12, v2
	v_cmp_eq_u32_e32 vcc, 0, v8
	v_add_u32_e32 v3, s13, v3
	v_add_u32_e32 v2, s12, v2
	v_lshl_add_u64 v[12:13], v[12:13], 2, s[8:9]
	v_lshl_add_u64 v[10:11], v[10:11], 2, s[8:9]
	s_or_b64 s[10:11], vcc, s[10:11]
	global_store_dword v[12:13], v7, off
	global_store_dword v[10:11], v7, off
	s_andn2_b64 exec, exec, s[10:11]
	s_cbranch_execnz .LBB0_99
	s_or_b64 exec, exec, s[10:11]
	v_mad_u64_u32 v[2:3], s[10:11], v5, s74, v[134:135]
	v_cmp_ne_u32_e32 vcc, v4, v5
	s_orn2_b64 s[10:11], vcc, exec

.LBB0_103:
	v_add_u32_e32 v2, s74, v2
	v_cmp_lt_i32_e32 vcc, s12, v2
	global_store_dword v[4:5], v3, off
	s_or_b64 s[10:11], vcc, s[10:11]
	v_lshl_add_u64 v[4:5], v[4:5], 0, s[0:1]
	s_andn2_b64 exec, exec, s[10:11]
	s_cbranch_execnz .LBB0_103

.LBB0_107:
	v_add_u32_e32 v8, -2, v8
	v_ashrrev_i32_e32 v11, 31, v3
	v_mov_b32_e32 v10, v3
	v_ashrrev_i32_e32 v13, 31, v2
	v_mov_b32_e32 v12, v2
	v_cmp_eq_u32_e32 vcc, 0, v8
	v_add_u32_e32 v3, s15, v3
	v_add_u32_e32 v2, s14, v2
	v_lshl_add_u64 v[12:13], v[12:13], 2, s[10:11]
	v_lshl_add_u64 v[10:11], v[10:11], 2, s[10:11]
	s_or_b64 s[12:13], vcc, s[12:13]
	global_store_dword v[12:13], v7, off
	global_store_dword v[10:11], v7, off
	s_andn2_b64 exec, exec, s[12:13]
	s_cbranch_execnz .LBB0_107
	s_or_b64 exec, exec, s[12:13]
	v_mad_u64_u32 v[2:3], s[10:11], v5, s74, v[134:135]
	v_cmp_ne_u32_e32 vcc, v4, v5
	s_orn2_b64 s[10:11], vcc, exec

.LBB0_115:
	v_add_u32_e32 v7, -2, v7
	v_ashrrev_i32_e32 v9, 31, v3
	v_mov_b32_e32 v8, v3
	v_ashrrev_i32_e32 v11, 31, v2
	v_mov_b32_e32 v10, v2
	v_cmp_eq_u32_e32 vcc, 0, v7
	v_add_u32_e32 v3, s15, v3
	v_add_u32_e32 v2, s14, v2
	v_lshl_add_u64 v[10:11], v[10:11], 2, s[10:11]
	v_lshl_add_u64 v[8:9], v[8:9], 2, s[10:11]
	s_or_b64 s[12:13], vcc, s[12:13]
	global_store_dword v[10:11], v6, off
	global_store_dword v[8:9], v6, off
	s_andn2_b64 exec, exec, s[12:13]
	s_cbranch_execnz .LBB0_115
	s_or_b64 exec, exec, s[12:13]
	v_mad_u64_u32 v[2:3], s[10:11], v5, s74, v[134:135]
	v_cmp_ne_u32_e32 vcc, v4, v5
	s_orn2_b64 s[10:11], vcc, exec

.LBB0_119:
	v_add_u32_e32 v2, s74, v2
	v_cmp_lt_i32_e32 vcc, s10, v2
	global_store_dword v[4:5], v3, off
	s_or_b64 s[8:9], vcc, s[8:9]
	v_lshl_add_u64 v[4:5], v[4:5], 0, s[0:1]
	s_andn2_b64 exec, exec, s[8:9]
	s_cbranch_execnz .LBB0_119
